# MFMA issue order in all 6 GEMM K-loops: accumulate chains (k0,k1) adjacent, m-outer across both blocks of a super-phase
# speedup vs baseline: 1.6100x; 1.6100x over previous
.LBB0_251:
	ds_read_b128 v[154:157], v151
	ds_read_b128 v[158:161], v151 offset:1024
	ds_read_b128 v[162:165], v151 offset:2048
	ds_read_b128 v[166:169], v151 offset:3072
	ds_read_b128 v[170:173], v152
	ds_read_b128 v[174:177], v152 offset:1024
	ds_read_b128 v[178:181], v152 offset:2048
	ds_read_b128 v[186:189], v152 offset:3072
	s_add_u32 s38, s36, 0xfff80080
	s_addc_u32 s39, s37, -1
	s_cmp_eq_u32 s74, 28
	s_cselect_b32 s45, s25, s39
	s_cselect_b32 s44, s34, s38
	s_cselect_b32 s39, s23, s71
	s_cselect_b32 s38, s35, s70
	v_lshl_add_u64 v[182:183], s[36:37], 0, v[142:143]
	s_add_i32 m0, s31, 0xc000
	ds_read_b128 v[190:193], v153
	ds_read_b128 v[194:197], v153 offset:1024
	ds_read_b128 v[202:205], v153 offset:2048
	ds_read_b128 v[206:209], v153 offset:3072
	ds_read_b128 v[210:213], v153 offset:4096
	ds_read_b128 v[214:217], v153 offset:5120
	ds_read_b128 v[226:229], v153 offset:6144
	ds_read_b128 v[230:233], v153 offset:7168
	global_load_lds_dwordx4 v[182:183], off
	v_lshl_add_u64 v[182:183], s[36:37], 0, v[140:141]
	s_add_i32 m0, s31, 0xe000
	s_nop 0
	global_load_lds_dwordx4 v[182:183], off
	s_waitcnt vmcnt(8)
	s_waitcnt lgkmcnt(0)
	s_barrier
	s_setprio 1
	s_waitcnt lgkmcnt(0)
	v_mfma_f32_16x16x32_bf16 v[126:129], v[154:157], v[190:193], v[126:129]
	v_mfma_f32_16x16x32_bf16 v[126:129], v[158:161], v[194:197], v[126:129]
	v_mfma_f32_16x16x32_bf16 v[122:125], v[162:165], v[190:193], v[122:125]
	v_mfma_f32_16x16x32_bf16 v[122:125], v[166:169], v[194:197], v[122:125]
	v_mfma_f32_16x16x32_bf16 v[118:121], v[170:173], v[190:193], v[118:121]
	v_mfma_f32_16x16x32_bf16 v[118:121], v[174:177], v[194:197], v[118:121]
	v_mfma_f32_16x16x32_bf16 v[114:117], v[178:181], v[190:193], v[114:117]
	v_mfma_f32_16x16x32_bf16 v[114:117], v[186:189], v[194:197], v[114:117]
	v_mfma_f32_16x16x32_bf16 v[110:113], v[154:157], v[202:205], v[110:113]
	v_mfma_f32_16x16x32_bf16 v[110:113], v[158:161], v[206:209], v[110:113]
	v_mfma_f32_16x16x32_bf16 v[106:109], v[162:165], v[202:205], v[106:109]
	v_mfma_f32_16x16x32_bf16 v[106:109], v[166:169], v[206:209], v[106:109]
	v_mfma_f32_16x16x32_bf16 v[102:105], v[170:173], v[202:205], v[102:105]
	v_mfma_f32_16x16x32_bf16 v[102:105], v[174:177], v[206:209], v[102:105]
	v_mfma_f32_16x16x32_bf16 v[98:101], v[178:181], v[202:205], v[98:101]
	v_mfma_f32_16x16x32_bf16 v[98:101], v[186:189], v[206:209], v[98:101]
	s_setprio 0
	s_setprio 1
	v_mfma_f32_16x16x32_bf16 v[94:97], v[154:157], v[210:213], v[94:97]
	v_mfma_f32_16x16x32_bf16 v[94:97], v[158:161], v[214:217], v[94:97]
	v_mfma_f32_16x16x32_bf16 v[90:93], v[162:165], v[210:213], v[90:93]
	v_mfma_f32_16x16x32_bf16 v[90:93], v[166:169], v[214:217], v[90:93]
	v_mfma_f32_16x16x32_bf16 v[86:89], v[170:173], v[210:213], v[86:89]
	v_mfma_f32_16x16x32_bf16 v[86:89], v[174:177], v[214:217], v[86:89]
	v_mfma_f32_16x16x32_bf16 v[82:85], v[178:181], v[210:213], v[82:85]
	v_mfma_f32_16x16x32_bf16 v[82:85], v[186:189], v[214:217], v[82:85]
	v_mfma_f32_16x16x32_bf16 v[78:81], v[154:157], v[226:229], v[78:81]
	v_mfma_f32_16x16x32_bf16 v[78:81], v[158:161], v[230:233], v[78:81]
	v_mfma_f32_16x16x32_bf16 v[74:77], v[162:165], v[226:229], v[74:77]
	v_mfma_f32_16x16x32_bf16 v[74:77], v[166:169], v[230:233], v[74:77]
	v_mfma_f32_16x16x32_bf16 v[70:73], v[170:173], v[226:229], v[70:73]
	v_mfma_f32_16x16x32_bf16 v[70:73], v[174:177], v[230:233], v[70:73]
	v_mfma_f32_16x16x32_bf16 v[66:69], v[178:181], v[226:229], v[66:69]
	v_mfma_f32_16x16x32_bf16 v[66:69], v[186:189], v[230:233], v[66:69]
	s_setprio 0
	s_barrier
	s_add_i32 s76, s66, s53
	v_lshl_add_u64 v[182:183], s[38:39], 0, v[134:135]
	s_mov_b32 m0, s76
	ds_read_b128 v[190:193], v153 offset:16384
	ds_read_b128 v[194:197], v153 offset:17408
	ds_read_b128 v[202:205], v153 offset:18432
	ds_read_b128 v[206:209], v153 offset:19456
	ds_read_b128 v[210:213], v153 offset:20480
	ds_read_b128 v[214:217], v153 offset:21504
	ds_read_b128 v[226:229], v153 offset:22528
	ds_read_b128 v[230:233], v153 offset:23552
	global_load_lds_dwordx4 v[182:183], off
	s_add_i32 m0, s76, 0x2000
	s_add_u32 s76, s38, 0x80000
	v_lshl_add_u64 v[234:235], s[38:39], 0, v[130:131]
	s_addc_u32 s77, s39, 0
	s_add_i32 s78, s67, s53
	global_load_lds_dwordx4 v[234:235], off
	v_lshl_add_u64 v[236:237], s[76:77], 0, v[134:135]
	s_mov_b32 m0, s78
	v_lshl_add_u64 v[238:239], s[44:45], 0, v[132:133]
	global_load_lds_dwordx4 v[236:237], off
	v_lshl_add_u64 v[236:237], s[76:77], 0, v[130:131]
	s_add_i32 m0, s78, 0x2000
	s_nop 0
	global_load_lds_dwordx4 v[236:237], off
	v_lshl_add_u64 v[236:237], s[44:45], 0, v[136:137]
	s_mov_b32 m0, s31
	s_nop 0
	global_load_lds_dwordx4 v[236:237], off
	s_mov_b32 m0, s56
	s_nop 0
	global_load_lds_dwordx4 v[238:239], off
	s_waitcnt vmcnt(8)
	s_waitcnt lgkmcnt(0)
	s_barrier
	s_setprio 1
	s_waitcnt lgkmcnt(0)
	v_mfma_f32_16x16x32_bf16 v[62:65], v[154:157], v[190:193], v[62:65]
	v_mfma_f32_16x16x32_bf16 v[62:65], v[158:161], v[194:197], v[62:65]
	v_mfma_f32_16x16x32_bf16 v[58:61], v[162:165], v[190:193], v[58:61]
	v_mfma_f32_16x16x32_bf16 v[58:61], v[166:169], v[194:197], v[58:61]
	v_mfma_f32_16x16x32_bf16 v[54:57], v[170:173], v[190:193], v[54:57]
	v_mfma_f32_16x16x32_bf16 v[54:57], v[174:177], v[194:197], v[54:57]
	v_mfma_f32_16x16x32_bf16 v[50:53], v[178:181], v[190:193], v[50:53]
	v_mfma_f32_16x16x32_bf16 v[50:53], v[186:189], v[194:197], v[50:53]
	v_mfma_f32_16x16x32_bf16 v[46:49], v[154:157], v[202:205], v[46:49]
	v_mfma_f32_16x16x32_bf16 v[46:49], v[158:161], v[206:209], v[46:49]
	v_mfma_f32_16x16x32_bf16 v[42:45], v[162:165], v[202:205], v[42:45]
	v_mfma_f32_16x16x32_bf16 v[42:45], v[166:169], v[206:209], v[42:45]
	v_mfma_f32_16x16x32_bf16 v[38:41], v[170:173], v[202:205], v[38:41]
	v_mfma_f32_16x16x32_bf16 v[38:41], v[174:177], v[206:209], v[38:41]
	v_mfma_f32_16x16x32_bf16 v[34:37], v[178:181], v[202:205], v[34:37]
	v_mfma_f32_16x16x32_bf16 v[34:37], v[186:189], v[206:209], v[34:37]
	s_setprio 0
	s_setprio 1
	v_mfma_f32_16x16x32_bf16 v[30:33], v[154:157], v[210:213], v[30:33]
	v_mfma_f32_16x16x32_bf16 v[30:33], v[158:161], v[214:217], v[30:33]
	v_mfma_f32_16x16x32_bf16 v[26:29], v[162:165], v[210:213], v[26:29]
	v_mfma_f32_16x16x32_bf16 v[26:29], v[166:169], v[214:217], v[26:29]
	v_mfma_f32_16x16x32_bf16 v[22:25], v[170:173], v[210:213], v[22:25]
	v_mfma_f32_16x16x32_bf16 v[22:25], v[174:177], v[214:217], v[22:25]
	v_mfma_f32_16x16x32_bf16 v[18:21], v[178:181], v[210:213], v[18:21]
	v_mfma_f32_16x16x32_bf16 v[18:21], v[186:189], v[214:217], v[18:21]
	v_mfma_f32_16x16x32_bf16 v[14:17], v[154:157], v[226:229], v[14:17]
	v_mfma_f32_16x16x32_bf16 v[14:17], v[158:161], v[230:233], v[14:17]
	v_mfma_f32_16x16x32_bf16 v[10:13], v[162:165], v[226:229], v[10:13]
	v_mfma_f32_16x16x32_bf16 v[10:13], v[166:169], v[230:233], v[10:13]
	v_mfma_f32_16x16x32_bf16 v[6:9], v[170:173], v[226:229], v[6:9]
	v_mfma_f32_16x16x32_bf16 v[6:9], v[174:177], v[230:233], v[6:9]
	v_mfma_f32_16x16x32_bf16 v[2:5], v[178:181], v[226:229], v[2:5]
	v_mfma_f32_16x16x32_bf16 v[2:5], v[186:189], v[230:233], v[2:5]
	s_setprio 0
	s_barrier
	s_add_i32 s76, 16, 0x18000
	v_add_u32_e32 v138, s76, v150
	s_add_i32 s77, 16, 0x1c000
	ds_read_b128 v[154:157], v138
	ds_read_b128 v[158:161], v138 offset:1024
	ds_read_b128 v[162:165], v138 offset:2048
	ds_read_b128 v[166:169], v138 offset:3072
	v_add_u32_e32 v138, s77, v150
	ds_read_b128 v[170:173], v138
	ds_read_b128 v[174:177], v138 offset:1024
	ds_read_b128 v[178:181], v138 offset:2048
	ds_read_b128 v[186:189], v138 offset:3072
	s_add_u32 s44, s44, 0x80000
	s_addc_u32 s45, s45, 0
	s_mov_b32 m0, s57
	v_lshl_add_u64 v[240:241], s[44:45], 0, v[136:137]
	ds_read_b128 v[190:193], v153 offset:32768
	ds_read_b128 v[194:197], v153 offset:33792
	ds_read_b128 v[202:205], v153 offset:34816
	ds_read_b128 v[206:209], v153 offset:35840
	ds_read_b128 v[210:213], v153 offset:36864
	ds_read_b128 v[214:217], v153 offset:37888
	ds_read_b128 v[226:229], v153 offset:38912
	ds_read_b128 v[230:233], v153 offset:39936
	global_load_lds_dwordx4 v[240:241], off
	v_lshl_add_u64 v[240:241], s[44:45], 0, v[132:133]
	s_mov_b32 m0, s58
	s_nop 0
	global_load_lds_dwordx4 v[240:241], off
	s_waitcnt vmcnt(8)
	s_waitcnt lgkmcnt(0)
	s_barrier
	s_setprio 1
	s_waitcnt lgkmcnt(0)
	v_mfma_f32_16x16x32_bf16 v[126:129], v[154:157], v[190:193], v[126:129]
	v_mfma_f32_16x16x32_bf16 v[126:129], v[158:161], v[194:197], v[126:129]
	v_mfma_f32_16x16x32_bf16 v[122:125], v[162:165], v[190:193], v[122:125]
	v_mfma_f32_16x16x32_bf16 v[122:125], v[166:169], v[194:197], v[122:125]
	v_mfma_f32_16x16x32_bf16 v[118:121], v[170:173], v[190:193], v[118:121]
	v_mfma_f32_16x16x32_bf16 v[118:121], v[174:177], v[194:197], v[118:121]
	v_mfma_f32_16x16x32_bf16 v[114:117], v[178:181], v[190:193], v[114:117]
	v_mfma_f32_16x16x32_bf16 v[114:117], v[186:189], v[194:197], v[114:117]
	v_mfma_f32_16x16x32_bf16 v[110:113], v[154:157], v[202:205], v[110:113]
	v_mfma_f32_16x16x32_bf16 v[110:113], v[158:161], v[206:209], v[110:113]
	v_mfma_f32_16x16x32_bf16 v[106:109], v[162:165], v[202:205], v[106:109]
	v_mfma_f32_16x16x32_bf16 v[106:109], v[166:169], v[206:209], v[106:109]
	v_mfma_f32_16x16x32_bf16 v[102:105], v[170:173], v[202:205], v[102:105]
	v_mfma_f32_16x16x32_bf16 v[102:105], v[174:177], v[206:209], v[102:105]
	v_mfma_f32_16x16x32_bf16 v[98:101], v[178:181], v[202:205], v[98:101]
	v_mfma_f32_16x16x32_bf16 v[98:101], v[186:189], v[206:209], v[98:101]
	s_setprio 0
	s_setprio 1
	v_mfma_f32_16x16x32_bf16 v[94:97], v[154:157], v[210:213], v[94:97]
	v_mfma_f32_16x16x32_bf16 v[94:97], v[158:161], v[214:217], v[94:97]
	v_mfma_f32_16x16x32_bf16 v[90:93], v[162:165], v[210:213], v[90:93]
	v_mfma_f32_16x16x32_bf16 v[90:93], v[166:169], v[214:217], v[90:93]
	v_mfma_f32_16x16x32_bf16 v[86:89], v[170:173], v[210:213], v[86:89]
	v_mfma_f32_16x16x32_bf16 v[86:89], v[174:177], v[214:217], v[86:89]
	v_mfma_f32_16x16x32_bf16 v[82:85], v[178:181], v[210:213], v[82:85]
	v_mfma_f32_16x16x32_bf16 v[82:85], v[186:189], v[214:217], v[82:85]
	v_mfma_f32_16x16x32_bf16 v[78:81], v[154:157], v[226:229], v[78:81]
	v_mfma_f32_16x16x32_bf16 v[78:81], v[158:161], v[230:233], v[78:81]
	v_mfma_f32_16x16x32_bf16 v[74:77], v[162:165], v[226:229], v[74:77]
	v_mfma_f32_16x16x32_bf16 v[74:77], v[166:169], v[230:233], v[74:77]
	v_mfma_f32_16x16x32_bf16 v[70:73], v[170:173], v[226:229], v[70:73]
	v_mfma_f32_16x16x32_bf16 v[70:73], v[174:177], v[230:233], v[70:73]
	v_mfma_f32_16x16x32_bf16 v[66:69], v[178:181], v[226:229], v[66:69]
	v_mfma_f32_16x16x32_bf16 v[66:69], v[186:189], v[230:233], v[66:69]
	s_setprio 0
	s_barrier
	s_add_i32 s44, s76, s53
	v_lshl_add_u64 v[182:183], v[182:183], 0, s[18:19]
	s_mov_b32 m0, s44
	ds_read_b128 v[190:193], v153 offset:49152
	ds_read_b128 v[194:197], v153 offset:50176
	ds_read_b128 v[202:205], v153 offset:51200
	ds_read_b128 v[206:209], v153 offset:52224
	ds_read_b128 v[210:213], v153 offset:53248
	ds_read_b128 v[214:217], v153 offset:54272
	ds_read_b128 v[226:229], v153 offset:55296
	ds_read_b128 v[230:233], v153 offset:56320
	global_load_lds_dwordx4 v[182:183], off
	s_add_i32 m0, s44, 0x2000
	s_add_u32 s38, s38, 0x80080
	v_lshl_add_u64 v[182:183], v[234:235], 0, s[18:19]
	s_addc_u32 s39, s39, 0
	s_add_i32 s44, s77, s53
	global_load_lds_dwordx4 v[182:183], off
	v_lshl_add_u64 v[182:183], s[38:39], 0, v[134:135]
	s_mov_b32 m0, s44
	s_nop 0
	global_load_lds_dwordx4 v[182:183], off
	v_lshl_add_u64 v[182:183], s[38:39], 0, v[130:131]
	s_add_i32 m0, s44, 0x2000
	s_nop 0
	global_load_lds_dwordx4 v[182:183], off
	v_lshl_add_u64 v[182:183], v[236:237], 0, s[18:19]
	s_mov_b32 m0, s62
	s_nop 0
	global_load_lds_dwordx4 v[182:183], off
	v_lshl_add_u64 v[182:183], v[238:239], 0, s[18:19]
	s_mov_b32 m0, s63
	s_nop 0
	global_load_lds_dwordx4 v[182:183], off
	s_waitcnt vmcnt(8)
	s_waitcnt lgkmcnt(0)
	s_barrier
	s_setprio 1
	s_waitcnt lgkmcnt(0)
	v_mfma_f32_16x16x32_bf16 v[62:65], v[154:157], v[190:193], v[62:65]
	v_mfma_f32_16x16x32_bf16 v[62:65], v[158:161], v[194:197], v[62:65]
	v_mfma_f32_16x16x32_bf16 v[58:61], v[162:165], v[190:193], v[58:61]
	v_mfma_f32_16x16x32_bf16 v[58:61], v[166:169], v[194:197], v[58:61]
	v_mfma_f32_16x16x32_bf16 v[54:57], v[170:173], v[190:193], v[54:57]
	v_mfma_f32_16x16x32_bf16 v[54:57], v[174:177], v[194:197], v[54:57]
	v_mfma_f32_16x16x32_bf16 v[50:53], v[178:181], v[190:193], v[50:53]
	v_mfma_f32_16x16x32_bf16 v[50:53], v[186:189], v[194:197], v[50:53]
	v_mfma_f32_16x16x32_bf16 v[46:49], v[154:157], v[202:205], v[46:49]
	v_mfma_f32_16x16x32_bf16 v[46:49], v[158:161], v[206:209], v[46:49]
	v_mfma_f32_16x16x32_bf16 v[42:45], v[162:165], v[202:205], v[42:45]
	v_mfma_f32_16x16x32_bf16 v[42:45], v[166:169], v[206:209], v[42:45]
	v_mfma_f32_16x16x32_bf16 v[38:41], v[170:173], v[202:205], v[38:41]
	v_mfma_f32_16x16x32_bf16 v[38:41], v[174:177], v[206:209], v[38:41]
	v_mfma_f32_16x16x32_bf16 v[34:37], v[178:181], v[202:205], v[34:37]
	v_mfma_f32_16x16x32_bf16 v[34:37], v[186:189], v[206:209], v[34:37]
	s_setprio 0
	s_setprio 1
	v_mfma_f32_16x16x32_bf16 v[30:33], v[154:157], v[210:213], v[30:33]
	v_mfma_f32_16x16x32_bf16 v[30:33], v[158:161], v[214:217], v[30:33]
	v_mfma_f32_16x16x32_bf16 v[26:29], v[162:165], v[210:213], v[26:29]
	v_mfma_f32_16x16x32_bf16 v[26:29], v[166:169], v[214:217], v[26:29]
	v_mfma_f32_16x16x32_bf16 v[22:25], v[170:173], v[210:213], v[22:25]
	v_mfma_f32_16x16x32_bf16 v[22:25], v[174:177], v[214:217], v[22:25]
	v_mfma_f32_16x16x32_bf16 v[18:21], v[178:181], v[210:213], v[18:21]
	v_mfma_f32_16x16x32_bf16 v[18:21], v[186:189], v[214:217], v[18:21]
	v_mfma_f32_16x16x32_bf16 v[14:17], v[154:157], v[226:229], v[14:17]
	v_mfma_f32_16x16x32_bf16 v[14:17], v[158:161], v[230:233], v[14:17]
	v_mfma_f32_16x16x32_bf16 v[10:13], v[162:165], v[226:229], v[10:13]
	v_mfma_f32_16x16x32_bf16 v[10:13], v[166:169], v[230:233], v[10:13]
	v_mfma_f32_16x16x32_bf16 v[6:9], v[170:173], v[226:229], v[6:9]
	v_mfma_f32_16x16x32_bf16 v[6:9], v[174:177], v[230:233], v[6:9]
	v_mfma_f32_16x16x32_bf16 v[2:5], v[178:181], v[226:229], v[2:5]
	v_mfma_f32_16x16x32_bf16 v[2:5], v[186:189], v[230:233], v[2:5]
	s_setprio 0
	s_barrier
	s_add_i32 s74, s74, 2
	s_add_u32 s70, s70, 0x100
	s_addc_u32 s71, s71, 0
	s_add_u32 s36, s36, 0x100
	s_addc_u32 s37, s37, 0
	s_cmp_gt_u32 s74, 29
	s_cbranch_scc0 .LBB0_251
	s_and_b64 vcc, exec, s[20:21]
	s_cbranch_vccz .LBB0_254
	s_barrier

.LBB0_335:
	ds_read_b128 v[130:133], v165
	ds_read_b128 v[134:137], v165 offset:1024
	ds_read_b128 v[138:141], v165 offset:2048
	ds_read_b128 v[142:145], v165 offset:3072
	ds_read_b128 v[168:171], v166
	ds_read_b128 v[172:175], v166 offset:1024
	ds_read_b128 v[176:179], v166 offset:2048
	ds_read_b128 v[180:183], v166 offset:3072
	s_add_u32 s64, s62, 0x100
	s_addc_u32 s65, s63, 0
	s_cmpk_eq_i32 s95, 0x52
	s_cselect_b32 s69, s9, s65
	s_cselect_b32 s68, s8, s64
	s_cselect_b32 s67, s61, s35
	s_cselect_b32 s66, s60, s34
	v_lshl_add_u64 v[160:161], s[62:63], 0, v[154:155]
	s_add_i32 m0, s78, 0xc000
	ds_read_b128 v[186:189], v167
	ds_read_b128 v[190:193], v167 offset:1024
	ds_read_b128 v[194:197], v167 offset:2048
	ds_read_b128 v[202:205], v167 offset:3072
	ds_read_b128 v[206:209], v167 offset:4096
	ds_read_b128 v[210:213], v167 offset:5120
	ds_read_b128 v[214:217], v167 offset:6144
	ds_read_b128 v[226:229], v167 offset:7168
	global_load_lds_dwordx4 v[160:161], off
	v_lshl_add_u64 v[160:161], s[62:63], 0, v[152:153]
	s_add_i32 m0, s78, 0xe000
	s_nop 0
	global_load_lds_dwordx4 v[160:161], off
	s_waitcnt vmcnt(8)
	s_waitcnt lgkmcnt(0)
	s_barrier
	s_setprio 1
	s_waitcnt lgkmcnt(0)
	v_mfma_f32_16x16x32_bf16 v[126:129], v[130:133], v[186:189], v[126:129]
	v_mfma_f32_16x16x32_bf16 v[126:129], v[134:137], v[190:193], v[126:129]
	v_mfma_f32_16x16x32_bf16 v[122:125], v[138:141], v[186:189], v[122:125]
	v_mfma_f32_16x16x32_bf16 v[122:125], v[142:145], v[190:193], v[122:125]
	v_mfma_f32_16x16x32_bf16 v[106:109], v[168:171], v[186:189], v[106:109]
	v_mfma_f32_16x16x32_bf16 v[106:109], v[172:175], v[190:193], v[106:109]
	v_mfma_f32_16x16x32_bf16 v[98:101], v[176:179], v[186:189], v[98:101]
	v_mfma_f32_16x16x32_bf16 v[98:101], v[180:183], v[190:193], v[98:101]
	v_mfma_f32_16x16x32_bf16 v[118:121], v[130:133], v[194:197], v[118:121]
	v_mfma_f32_16x16x32_bf16 v[118:121], v[134:137], v[202:205], v[118:121]
	v_mfma_f32_16x16x32_bf16 v[114:117], v[138:141], v[194:197], v[114:117]
	v_mfma_f32_16x16x32_bf16 v[114:117], v[142:145], v[202:205], v[114:117]
	v_mfma_f32_16x16x32_bf16 v[90:93], v[168:171], v[194:197], v[90:93]
	v_mfma_f32_16x16x32_bf16 v[90:93], v[172:175], v[202:205], v[90:93]
	v_mfma_f32_16x16x32_bf16 v[86:89], v[176:179], v[194:197], v[86:89]
	v_mfma_f32_16x16x32_bf16 v[86:89], v[180:183], v[202:205], v[86:89]
	s_setprio 0
	s_setprio 1
	v_mfma_f32_16x16x32_bf16 v[110:113], v[130:133], v[206:209], v[110:113]
	v_mfma_f32_16x16x32_bf16 v[110:113], v[134:137], v[210:213], v[110:113]
	v_mfma_f32_16x16x32_bf16 v[102:105], v[138:141], v[206:209], v[102:105]
	v_mfma_f32_16x16x32_bf16 v[102:105], v[142:145], v[210:213], v[102:105]
	v_mfma_f32_16x16x32_bf16 v[82:85], v[168:171], v[206:209], v[82:85]
	v_mfma_f32_16x16x32_bf16 v[82:85], v[172:175], v[210:213], v[82:85]
	v_mfma_f32_16x16x32_bf16 v[78:81], v[176:179], v[206:209], v[78:81]
	v_mfma_f32_16x16x32_bf16 v[78:81], v[180:183], v[210:213], v[78:81]
	v_mfma_f32_16x16x32_bf16 v[94:97], v[130:133], v[214:217], v[94:97]
	v_mfma_f32_16x16x32_bf16 v[94:97], v[134:137], v[226:229], v[94:97]
	v_mfma_f32_16x16x32_bf16 v[74:77], v[138:141], v[214:217], v[74:77]
	v_mfma_f32_16x16x32_bf16 v[74:77], v[142:145], v[226:229], v[74:77]
	v_mfma_f32_16x16x32_bf16 v[70:73], v[168:171], v[214:217], v[70:73]
	v_mfma_f32_16x16x32_bf16 v[70:73], v[172:175], v[226:229], v[70:73]
	v_mfma_f32_16x16x32_bf16 v[66:69], v[176:179], v[214:217], v[66:69]
	v_mfma_f32_16x16x32_bf16 v[66:69], v[180:183], v[226:229], v[66:69]
	s_setprio 0
	s_barrier
	s_add_i32 s52, s89, s70
	v_lshl_add_u64 v[160:161], s[66:67], 0, v[148:149]
	s_mov_b32 m0, s52
	ds_read_b128 v[186:189], v167 offset:16384
	ds_read_b128 v[190:193], v167 offset:17408
	ds_read_b128 v[194:197], v167 offset:18432
	ds_read_b128 v[202:205], v167 offset:19456
	ds_read_b128 v[206:209], v167 offset:20480
	ds_read_b128 v[210:213], v167 offset:21504
	ds_read_b128 v[214:217], v167 offset:22528
	ds_read_b128 v[226:229], v167 offset:23552
	global_load_lds_dwordx4 v[160:161], off
	s_add_i32 m0, s52, 0x2000
	s_add_u32 s62, s66, 0x158000
	v_lshl_add_u64 v[230:231], s[66:67], 0, v[146:147]
	s_addc_u32 s63, s67, 0
	s_add_i32 s52, s90, s70
	global_load_lds_dwordx4 v[230:231], off
	v_lshl_add_u64 v[232:233], s[62:63], 0, v[148:149]
	s_mov_b32 m0, s52
	v_lshl_add_u64 v[234:235], s[68:69], 0, v[146:147]
	global_load_lds_dwordx4 v[232:233], off
	v_lshl_add_u64 v[232:233], s[62:63], 0, v[146:147]
	s_add_i32 m0, s52, 0x2000
	s_nop 0
	global_load_lds_dwordx4 v[232:233], off
	v_lshl_add_u64 v[232:233], s[68:69], 0, v[148:149]
	s_mov_b32 m0, s78
	s_nop 0
	global_load_lds_dwordx4 v[232:233], off
	s_mov_b32 m0, s79
	s_nop 0
	global_load_lds_dwordx4 v[234:235], off
	s_waitcnt vmcnt(8)
	s_waitcnt lgkmcnt(0)
	s_barrier
	s_setprio 1
	s_waitcnt lgkmcnt(0)
	v_mfma_f32_16x16x32_bf16 v[62:65], v[130:133], v[186:189], v[62:65]
	v_mfma_f32_16x16x32_bf16 v[62:65], v[134:137], v[190:193], v[62:65]
	v_mfma_f32_16x16x32_bf16 v[58:61], v[138:141], v[186:189], v[58:61]
	v_mfma_f32_16x16x32_bf16 v[58:61], v[142:145], v[190:193], v[58:61]
	v_mfma_f32_16x16x32_bf16 v[42:45], v[168:171], v[186:189], v[42:45]
	v_mfma_f32_16x16x32_bf16 v[42:45], v[172:175], v[190:193], v[42:45]
	v_mfma_f32_16x16x32_bf16 v[34:37], v[176:179], v[186:189], v[34:37]
	v_mfma_f32_16x16x32_bf16 v[34:37], v[180:183], v[190:193], v[34:37]
	v_mfma_f32_16x16x32_bf16 v[54:57], v[130:133], v[194:197], v[54:57]
	v_mfma_f32_16x16x32_bf16 v[54:57], v[134:137], v[202:205], v[54:57]
	v_mfma_f32_16x16x32_bf16 v[50:53], v[138:141], v[194:197], v[50:53]
	v_mfma_f32_16x16x32_bf16 v[50:53], v[142:145], v[202:205], v[50:53]
	v_mfma_f32_16x16x32_bf16 v[26:29], v[168:171], v[194:197], v[26:29]
	v_mfma_f32_16x16x32_bf16 v[26:29], v[172:175], v[202:205], v[26:29]
	v_mfma_f32_16x16x32_bf16 v[22:25], v[176:179], v[194:197], v[22:25]
	v_mfma_f32_16x16x32_bf16 v[22:25], v[180:183], v[202:205], v[22:25]
	s_setprio 0
	s_setprio 1
	v_mfma_f32_16x16x32_bf16 v[46:49], v[130:133], v[206:209], v[46:49]
	v_mfma_f32_16x16x32_bf16 v[46:49], v[134:137], v[210:213], v[46:49]
	v_mfma_f32_16x16x32_bf16 v[38:41], v[138:141], v[206:209], v[38:41]
	v_mfma_f32_16x16x32_bf16 v[38:41], v[142:145], v[210:213], v[38:41]
	v_mfma_f32_16x16x32_bf16 v[18:21], v[168:171], v[206:209], v[18:21]
	v_mfma_f32_16x16x32_bf16 v[18:21], v[172:175], v[210:213], v[18:21]
	v_mfma_f32_16x16x32_bf16 v[14:17], v[176:179], v[206:209], v[14:17]
	v_mfma_f32_16x16x32_bf16 v[14:17], v[180:183], v[210:213], v[14:17]
	v_mfma_f32_16x16x32_bf16 v[30:33], v[130:133], v[214:217], v[30:33]
	v_mfma_f32_16x16x32_bf16 v[30:33], v[134:137], v[226:229], v[30:33]
	v_mfma_f32_16x16x32_bf16 v[10:13], v[138:141], v[214:217], v[10:13]
	v_mfma_f32_16x16x32_bf16 v[10:13], v[142:145], v[226:229], v[10:13]
	v_mfma_f32_16x16x32_bf16 v[6:9], v[168:171], v[214:217], v[6:9]
	v_mfma_f32_16x16x32_bf16 v[6:9], v[172:175], v[226:229], v[6:9]
	v_mfma_f32_16x16x32_bf16 v[2:5], v[176:179], v[214:217], v[2:5]
	v_mfma_f32_16x16x32_bf16 v[2:5], v[180:183], v[226:229], v[2:5]
	s_setprio 0
	s_barrier
	s_add_i32 s52, 16, 0x18000
	s_add_i32 s53, 16, 0x1c000
	v_add_u32_e32 v142, s52, v164
	v_add_u32_e32 v150, s53, v164
	ds_read_b128 v[130:133], v142
	ds_read_b128 v[134:137], v142 offset:1024
	ds_read_b128 v[138:141], v142 offset:2048
	ds_read_b128 v[142:145], v142 offset:3072
	ds_read_b128 v[168:171], v150
	ds_read_b128 v[172:175], v150 offset:1024
	ds_read_b128 v[176:179], v150 offset:2048
	ds_read_b128 v[180:183], v150 offset:3072
	s_add_u32 s62, s68, 0x158000
	s_addc_u32 s63, s69, 0
	s_mov_b32 m0, s80
	v_lshl_add_u64 v[236:237], s[62:63], 0, v[148:149]
	ds_read_b128 v[186:189], v167 offset:32768
	ds_read_b128 v[190:193], v167 offset:33792
	ds_read_b128 v[194:197], v167 offset:34816
	ds_read_b128 v[202:205], v167 offset:35840
	ds_read_b128 v[206:209], v167 offset:36864
	ds_read_b128 v[210:213], v167 offset:37888
	ds_read_b128 v[214:217], v167 offset:38912
	ds_read_b128 v[226:229], v167 offset:39936
	global_load_lds_dwordx4 v[236:237], off
	v_lshl_add_u64 v[236:237], s[62:63], 0, v[146:147]
	s_mov_b32 m0, s81
	s_nop 0
	global_load_lds_dwordx4 v[236:237], off
	s_waitcnt vmcnt(8)
	s_waitcnt lgkmcnt(0)
	s_barrier
	s_setprio 1
	s_waitcnt lgkmcnt(0)
	v_mfma_f32_16x16x32_bf16 v[126:129], v[130:133], v[186:189], v[126:129]
	v_mfma_f32_16x16x32_bf16 v[126:129], v[134:137], v[190:193], v[126:129]
	v_mfma_f32_16x16x32_bf16 v[122:125], v[138:141], v[186:189], v[122:125]
	v_mfma_f32_16x16x32_bf16 v[122:125], v[142:145], v[190:193], v[122:125]
	v_mfma_f32_16x16x32_bf16 v[106:109], v[168:171], v[186:189], v[106:109]
	v_mfma_f32_16x16x32_bf16 v[106:109], v[172:175], v[190:193], v[106:109]
	v_mfma_f32_16x16x32_bf16 v[98:101], v[176:179], v[186:189], v[98:101]
	v_mfma_f32_16x16x32_bf16 v[98:101], v[180:183], v[190:193], v[98:101]
	v_mfma_f32_16x16x32_bf16 v[118:121], v[130:133], v[194:197], v[118:121]
	v_mfma_f32_16x16x32_bf16 v[118:121], v[134:137], v[202:205], v[118:121]
	v_mfma_f32_16x16x32_bf16 v[114:117], v[138:141], v[194:197], v[114:117]
	v_mfma_f32_16x16x32_bf16 v[114:117], v[142:145], v[202:205], v[114:117]
	v_mfma_f32_16x16x32_bf16 v[90:93], v[168:171], v[194:197], v[90:93]
	v_mfma_f32_16x16x32_bf16 v[90:93], v[172:175], v[202:205], v[90:93]
	v_mfma_f32_16x16x32_bf16 v[86:89], v[176:179], v[194:197], v[86:89]
	v_mfma_f32_16x16x32_bf16 v[86:89], v[180:183], v[202:205], v[86:89]
	s_setprio 0
	s_setprio 1
	v_mfma_f32_16x16x32_bf16 v[110:113], v[130:133], v[206:209], v[110:113]
	v_mfma_f32_16x16x32_bf16 v[110:113], v[134:137], v[210:213], v[110:113]
	v_mfma_f32_16x16x32_bf16 v[102:105], v[138:141], v[206:209], v[102:105]
	v_mfma_f32_16x16x32_bf16 v[102:105], v[142:145], v[210:213], v[102:105]
	v_mfma_f32_16x16x32_bf16 v[82:85], v[168:171], v[206:209], v[82:85]
	v_mfma_f32_16x16x32_bf16 v[82:85], v[172:175], v[210:213], v[82:85]
	v_mfma_f32_16x16x32_bf16 v[78:81], v[176:179], v[206:209], v[78:81]
	v_mfma_f32_16x16x32_bf16 v[78:81], v[180:183], v[210:213], v[78:81]
	v_mfma_f32_16x16x32_bf16 v[94:97], v[130:133], v[214:217], v[94:97]
	v_mfma_f32_16x16x32_bf16 v[94:97], v[134:137], v[226:229], v[94:97]
	v_mfma_f32_16x16x32_bf16 v[74:77], v[138:141], v[214:217], v[74:77]
	v_mfma_f32_16x16x32_bf16 v[74:77], v[142:145], v[226:229], v[74:77]
	v_mfma_f32_16x16x32_bf16 v[70:73], v[168:171], v[214:217], v[70:73]
	v_mfma_f32_16x16x32_bf16 v[70:73], v[172:175], v[226:229], v[70:73]
	v_mfma_f32_16x16x32_bf16 v[66:69], v[176:179], v[214:217], v[66:69]
	v_mfma_f32_16x16x32_bf16 v[66:69], v[180:183], v[226:229], v[66:69]
	s_setprio 0
	s_barrier
	s_add_i32 s52, s52, s70
	v_lshl_add_u64 v[160:161], v[160:161], 0, s[56:57]
	s_mov_b32 m0, s52
	ds_read_b128 v[186:189], v167 offset:49152
	ds_read_b128 v[190:193], v167 offset:50176
	ds_read_b128 v[194:197], v167 offset:51200
	ds_read_b128 v[202:205], v167 offset:52224
	ds_read_b128 v[206:209], v167 offset:53248
	ds_read_b128 v[210:213], v167 offset:54272
	ds_read_b128 v[214:217], v167 offset:55296
	ds_read_b128 v[226:229], v167 offset:56320
	global_load_lds_dwordx4 v[160:161], off
	s_add_i32 m0, s52, 0x2000
	s_add_u32 s62, s66, 0x158080
	v_lshl_add_u64 v[160:161], v[230:231], 0, s[56:57]
	s_addc_u32 s63, s67, 0
	s_add_i32 s52, s53, s70
	global_load_lds_dwordx4 v[160:161], off
	v_lshl_add_u64 v[160:161], s[62:63], 0, v[148:149]
	s_mov_b32 m0, s52
	s_nop 0
	global_load_lds_dwordx4 v[160:161], off
	v_lshl_add_u64 v[160:161], s[62:63], 0, v[146:147]
	s_add_i32 m0, s52, 0x2000
	s_nop 0
	global_load_lds_dwordx4 v[160:161], off
	v_lshl_add_u64 v[160:161], v[232:233], 0, s[56:57]
	s_mov_b32 m0, s85
	s_nop 0
	global_load_lds_dwordx4 v[160:161], off
	v_lshl_add_u64 v[160:161], v[234:235], 0, s[56:57]
	s_mov_b32 m0, s86
	s_nop 0
	global_load_lds_dwordx4 v[160:161], off
	s_waitcnt vmcnt(8)
	s_waitcnt lgkmcnt(0)
	s_barrier
	s_setprio 1
	s_waitcnt lgkmcnt(0)
	v_mfma_f32_16x16x32_bf16 v[62:65], v[130:133], v[186:189], v[62:65]
	v_mfma_f32_16x16x32_bf16 v[62:65], v[134:137], v[190:193], v[62:65]
	v_mfma_f32_16x16x32_bf16 v[58:61], v[138:141], v[186:189], v[58:61]
	v_mfma_f32_16x16x32_bf16 v[58:61], v[142:145], v[190:193], v[58:61]
	v_mfma_f32_16x16x32_bf16 v[42:45], v[168:171], v[186:189], v[42:45]
	v_mfma_f32_16x16x32_bf16 v[42:45], v[172:175], v[190:193], v[42:45]
	v_mfma_f32_16x16x32_bf16 v[34:37], v[176:179], v[186:189], v[34:37]
	v_mfma_f32_16x16x32_bf16 v[34:37], v[180:183], v[190:193], v[34:37]
	v_mfma_f32_16x16x32_bf16 v[54:57], v[130:133], v[194:197], v[54:57]
	v_mfma_f32_16x16x32_bf16 v[54:57], v[134:137], v[202:205], v[54:57]
	v_mfma_f32_16x16x32_bf16 v[50:53], v[138:141], v[194:197], v[50:53]
	v_mfma_f32_16x16x32_bf16 v[50:53], v[142:145], v[202:205], v[50:53]
	v_mfma_f32_16x16x32_bf16 v[26:29], v[168:171], v[194:197], v[26:29]
	v_mfma_f32_16x16x32_bf16 v[26:29], v[172:175], v[202:205], v[26:29]
	v_mfma_f32_16x16x32_bf16 v[22:25], v[176:179], v[194:197], v[22:25]
	v_mfma_f32_16x16x32_bf16 v[22:25], v[180:183], v[202:205], v[22:25]
	s_setprio 0
	s_setprio 1
	v_mfma_f32_16x16x32_bf16 v[46:49], v[130:133], v[206:209], v[46:49]
	v_mfma_f32_16x16x32_bf16 v[46:49], v[134:137], v[210:213], v[46:49]
	v_mfma_f32_16x16x32_bf16 v[38:41], v[138:141], v[206:209], v[38:41]
	v_mfma_f32_16x16x32_bf16 v[38:41], v[142:145], v[210:213], v[38:41]
	v_mfma_f32_16x16x32_bf16 v[18:21], v[168:171], v[206:209], v[18:21]
	v_mfma_f32_16x16x32_bf16 v[18:21], v[172:175], v[210:213], v[18:21]
	v_mfma_f32_16x16x32_bf16 v[14:17], v[176:179], v[206:209], v[14:17]
	v_mfma_f32_16x16x32_bf16 v[14:17], v[180:183], v[210:213], v[14:17]
	v_mfma_f32_16x16x32_bf16 v[30:33], v[130:133], v[214:217], v[30:33]
	v_mfma_f32_16x16x32_bf16 v[30:33], v[134:137], v[226:229], v[30:33]
	v_mfma_f32_16x16x32_bf16 v[10:13], v[138:141], v[214:217], v[10:13]
	v_mfma_f32_16x16x32_bf16 v[10:13], v[142:145], v[226:229], v[10:13]
	v_mfma_f32_16x16x32_bf16 v[6:9], v[168:171], v[214:217], v[6:9]
	v_mfma_f32_16x16x32_bf16 v[6:9], v[172:175], v[226:229], v[6:9]
	v_mfma_f32_16x16x32_bf16 v[2:5], v[176:179], v[214:217], v[2:5]
	v_mfma_f32_16x16x32_bf16 v[2:5], v[180:183], v[226:229], v[2:5]
	s_setprio 0
	s_barrier
	s_add_i32 s95, s95, 2
	s_add_u32 s34, s34, 0x100
	s_addc_u32 s35, s35, 0
	s_cmpk_gt_u32 s95, 0x53
	s_mov_b64 s[62:63], s[64:65]
	s_cbranch_scc0 .LBB0_335
	s_and_b64 vcc, exec, s[58:59]
	s_cbranch_vccz .LBB0_338
	s_barrier

.LBB0_531:
	ds_read_b128 v[130:133], v188
	ds_read_b128 v[134:137], v188 offset:1024
	ds_read_b128 v[138:141], v188 offset:2048
	ds_read_b128 v[142:145], v188 offset:3072
	ds_read_b128 v[146:149], v189
	ds_read_b128 v[168:171], v189 offset:1024
	ds_read_b128 v[172:175], v189 offset:2048
	ds_read_b128 v[176:179], v189 offset:3072
	s_add_u32 s10, s8, 0xfff80080
	s_addc_u32 s11, s9, -1
	s_cmp_eq_u32 s69, 28
	s_cselect_b32 s67, s34, s11
	s_cselect_b32 s66, s35, s10
	s_cselect_b32 s11, s51, s68
	s_cselect_b32 s10, s59, s61
	v_lshl_add_u64 v[196:197], s[8:9], 0, v[162:163]
	s_add_i32 m0, s55, 0xc000
	ds_read_b128 v[180:183], v190
	ds_read_b128 v[202:205], v190 offset:1024
	ds_read_b128 v[206:209], v190 offset:2048
	ds_read_b128 v[210:213], v190 offset:3072
	ds_read_b128 v[214:217], v190 offset:4096
	ds_read_b128 v[226:229], v190 offset:5120
	ds_read_b128 v[230:233], v190 offset:6144
	ds_read_b128 v[234:237], v190 offset:7168
	global_load_lds_dwordx4 v[196:197], off
	v_lshl_add_u64 v[196:197], s[8:9], 0, v[160:161]
	s_add_i32 m0, s55, 0xe000
	s_nop 0
	global_load_lds_dwordx4 v[196:197], off
	s_waitcnt vmcnt(8)
	s_waitcnt lgkmcnt(0)
	s_barrier
	s_setprio 1
	s_waitcnt lgkmcnt(0)
	v_mfma_f32_16x16x32_bf16 v[126:129], v[130:133], v[180:183], v[126:129]
	v_mfma_f32_16x16x32_bf16 v[126:129], v[134:137], v[202:205], v[126:129]
	v_mfma_f32_16x16x32_bf16 v[122:125], v[138:141], v[180:183], v[122:125]
	v_mfma_f32_16x16x32_bf16 v[122:125], v[142:145], v[202:205], v[122:125]
	v_mfma_f32_16x16x32_bf16 v[118:121], v[146:149], v[180:183], v[118:121]
	v_mfma_f32_16x16x32_bf16 v[118:121], v[168:171], v[202:205], v[118:121]
	v_mfma_f32_16x16x32_bf16 v[110:113], v[172:175], v[180:183], v[110:113]
	v_mfma_f32_16x16x32_bf16 v[110:113], v[176:179], v[202:205], v[110:113]
	v_mfma_f32_16x16x32_bf16 v[114:117], v[130:133], v[206:209], v[114:117]
	v_mfma_f32_16x16x32_bf16 v[114:117], v[134:137], v[210:213], v[114:117]
	v_mfma_f32_16x16x32_bf16 v[106:109], v[138:141], v[206:209], v[106:109]
	v_mfma_f32_16x16x32_bf16 v[106:109], v[142:145], v[210:213], v[106:109]
	v_mfma_f32_16x16x32_bf16 v[102:105], v[146:149], v[206:209], v[102:105]
	v_mfma_f32_16x16x32_bf16 v[102:105], v[168:171], v[210:213], v[102:105]
	v_mfma_f32_16x16x32_bf16 v[94:97], v[172:175], v[206:209], v[94:97]
	v_mfma_f32_16x16x32_bf16 v[94:97], v[176:179], v[210:213], v[94:97]
	s_setprio 0
	s_setprio 1
	v_mfma_f32_16x16x32_bf16 v[98:101], v[130:133], v[214:217], v[98:101]
	v_mfma_f32_16x16x32_bf16 v[98:101], v[134:137], v[226:229], v[98:101]
	v_mfma_f32_16x16x32_bf16 v[90:93], v[138:141], v[214:217], v[90:93]
	v_mfma_f32_16x16x32_bf16 v[90:93], v[142:145], v[226:229], v[90:93]
	v_mfma_f32_16x16x32_bf16 v[86:89], v[146:149], v[214:217], v[86:89]
	v_mfma_f32_16x16x32_bf16 v[86:89], v[168:171], v[226:229], v[86:89]
	v_mfma_f32_16x16x32_bf16 v[78:81], v[172:175], v[214:217], v[78:81]
	v_mfma_f32_16x16x32_bf16 v[78:81], v[176:179], v[226:229], v[78:81]
	v_mfma_f32_16x16x32_bf16 v[82:85], v[130:133], v[230:233], v[82:85]
	v_mfma_f32_16x16x32_bf16 v[82:85], v[134:137], v[234:237], v[82:85]
	v_mfma_f32_16x16x32_bf16 v[74:77], v[138:141], v[230:233], v[74:77]
	v_mfma_f32_16x16x32_bf16 v[74:77], v[142:145], v[234:237], v[74:77]
	v_mfma_f32_16x16x32_bf16 v[70:73], v[146:149], v[230:233], v[70:73]
	v_mfma_f32_16x16x32_bf16 v[70:73], v[168:171], v[234:237], v[70:73]
	v_mfma_f32_16x16x32_bf16 v[66:69], v[172:175], v[230:233], v[66:69]
	v_mfma_f32_16x16x32_bf16 v[66:69], v[176:179], v[234:237], v[66:69]
	s_setprio 0
	s_barrier
	s_add_i32 s52, s96, s81
	v_lshl_add_u64 v[196:197], s[10:11], 0, v[152:153]
	s_mov_b32 m0, s52
	ds_read_b128 v[180:183], v190 offset:16384
	ds_read_b128 v[202:205], v190 offset:17408
	ds_read_b128 v[206:209], v190 offset:18432
	ds_read_b128 v[210:213], v190 offset:19456
	ds_read_b128 v[214:217], v190 offset:20480
	ds_read_b128 v[226:229], v190 offset:21504
	ds_read_b128 v[230:233], v190 offset:22528
	ds_read_b128 v[234:237], v190 offset:23552
	global_load_lds_dwordx4 v[196:197], off
	s_add_i32 m0, s52, 0x2000
	s_add_u32 s52, s10, 0x80000
	v_lshl_add_u64 v[238:239], s[10:11], 0, v[156:157]
	s_addc_u32 s53, s11, 0
	s_add_i32 s70, s97, s81
	global_load_lds_dwordx4 v[238:239], off
	v_lshl_add_u64 v[240:241], s[52:53], 0, v[152:153]
	s_mov_b32 m0, s70
	v_lshl_add_u64 v[242:243], s[66:67], 0, v[154:155]
	global_load_lds_dwordx4 v[240:241], off
	v_lshl_add_u64 v[240:241], s[52:53], 0, v[156:157]
	s_add_i32 m0, s70, 0x2000
	s_nop 0
	global_load_lds_dwordx4 v[240:241], off
	v_lshl_add_u64 v[240:241], s[66:67], 0, v[150:151]
	s_mov_b32 m0, s55
	s_nop 0
	global_load_lds_dwordx4 v[240:241], off
	s_mov_b32 m0, s57
	s_nop 0
	global_load_lds_dwordx4 v[242:243], off
	s_waitcnt vmcnt(8)
	s_waitcnt lgkmcnt(0)
	s_barrier
	s_setprio 1
	s_waitcnt lgkmcnt(0)
	v_mfma_f32_16x16x32_bf16 v[62:65], v[130:133], v[180:183], v[62:65]
	v_mfma_f32_16x16x32_bf16 v[62:65], v[134:137], v[202:205], v[62:65]
	v_mfma_f32_16x16x32_bf16 v[58:61], v[138:141], v[180:183], v[58:61]
	v_mfma_f32_16x16x32_bf16 v[58:61], v[142:145], v[202:205], v[58:61]
	v_mfma_f32_16x16x32_bf16 v[50:53], v[146:149], v[180:183], v[50:53]
	v_mfma_f32_16x16x32_bf16 v[50:53], v[168:171], v[202:205], v[50:53]
	v_mfma_f32_16x16x32_bf16 v[42:45], v[172:175], v[180:183], v[42:45]
	v_mfma_f32_16x16x32_bf16 v[42:45], v[176:179], v[202:205], v[42:45]
	v_mfma_f32_16x16x32_bf16 v[54:57], v[130:133], v[206:209], v[54:57]
	v_mfma_f32_16x16x32_bf16 v[54:57], v[134:137], v[210:213], v[54:57]
	v_mfma_f32_16x16x32_bf16 v[46:49], v[138:141], v[206:209], v[46:49]
	v_mfma_f32_16x16x32_bf16 v[46:49], v[142:145], v[210:213], v[46:49]
	v_mfma_f32_16x16x32_bf16 v[34:37], v[146:149], v[206:209], v[34:37]
	v_mfma_f32_16x16x32_bf16 v[34:37], v[168:171], v[210:213], v[34:37]
	v_mfma_f32_16x16x32_bf16 v[26:29], v[172:175], v[206:209], v[26:29]
	v_mfma_f32_16x16x32_bf16 v[26:29], v[176:179], v[210:213], v[26:29]
	s_setprio 0
	s_setprio 1
	v_mfma_f32_16x16x32_bf16 v[38:41], v[130:133], v[214:217], v[38:41]
	v_mfma_f32_16x16x32_bf16 v[38:41], v[134:137], v[226:229], v[38:41]
	v_mfma_f32_16x16x32_bf16 v[30:33], v[138:141], v[214:217], v[30:33]
	v_mfma_f32_16x16x32_bf16 v[30:33], v[142:145], v[226:229], v[30:33]
	v_mfma_f32_16x16x32_bf16 v[18:21], v[146:149], v[214:217], v[18:21]
	v_mfma_f32_16x16x32_bf16 v[18:21], v[168:171], v[226:229], v[18:21]
	v_mfma_f32_16x16x32_bf16 v[10:13], v[172:175], v[214:217], v[10:13]
	v_mfma_f32_16x16x32_bf16 v[10:13], v[176:179], v[226:229], v[10:13]
	v_mfma_f32_16x16x32_bf16 v[22:25], v[130:133], v[230:233], v[22:25]
	v_mfma_f32_16x16x32_bf16 v[22:25], v[134:137], v[234:237], v[22:25]
	v_mfma_f32_16x16x32_bf16 v[14:17], v[138:141], v[230:233], v[14:17]
	v_mfma_f32_16x16x32_bf16 v[14:17], v[142:145], v[234:237], v[14:17]
	v_mfma_f32_16x16x32_bf16 v[6:9], v[146:149], v[230:233], v[6:9]
	v_mfma_f32_16x16x32_bf16 v[6:9], v[168:171], v[234:237], v[6:9]
	v_mfma_f32_16x16x32_bf16 v[2:5], v[172:175], v[230:233], v[2:5]
	v_mfma_f32_16x16x32_bf16 v[2:5], v[176:179], v[234:237], v[2:5]
	s_setprio 0
	s_barrier
	s_add_i32 s70, 16, 0x18000
	s_add_i32 s71, 16, 0x1c000
	v_add_u32_e32 v142, s70, v187
	v_add_u32_e32 v158, s71, v187
	ds_read_b128 v[130:133], v142
	ds_read_b128 v[134:137], v142 offset:1024
	ds_read_b128 v[138:141], v142 offset:2048
	ds_read_b128 v[142:145], v142 offset:3072
	ds_read_b128 v[146:149], v158
	ds_read_b128 v[168:171], v158 offset:1024
	ds_read_b128 v[172:175], v158 offset:2048
	ds_read_b128 v[176:179], v158 offset:3072
	s_add_u32 s52, s66, 0x80000
	s_addc_u32 s53, s67, 0
	s_mov_b32 m0, s82
	v_lshl_add_u64 v[244:245], s[52:53], 0, v[150:151]
	ds_read_b128 v[180:183], v190 offset:32768
	ds_read_b128 v[202:205], v190 offset:33792
	ds_read_b128 v[206:209], v190 offset:34816
	ds_read_b128 v[210:213], v190 offset:35840
	ds_read_b128 v[214:217], v190 offset:36864
	ds_read_b128 v[226:229], v190 offset:37888
	ds_read_b128 v[230:233], v190 offset:38912
	ds_read_b128 v[234:237], v190 offset:39936
	global_load_lds_dwordx4 v[244:245], off
	v_lshl_add_u64 v[244:245], s[52:53], 0, v[154:155]
	s_mov_b32 m0, s83
	s_nop 0
	global_load_lds_dwordx4 v[244:245], off
	s_waitcnt vmcnt(8)
	s_waitcnt lgkmcnt(0)
	s_barrier
	s_setprio 1
	s_waitcnt lgkmcnt(0)
	v_mfma_f32_16x16x32_bf16 v[126:129], v[130:133], v[180:183], v[126:129]
	v_mfma_f32_16x16x32_bf16 v[126:129], v[134:137], v[202:205], v[126:129]
	v_mfma_f32_16x16x32_bf16 v[122:125], v[138:141], v[180:183], v[122:125]
	v_mfma_f32_16x16x32_bf16 v[122:125], v[142:145], v[202:205], v[122:125]
	v_mfma_f32_16x16x32_bf16 v[118:121], v[146:149], v[180:183], v[118:121]
	v_mfma_f32_16x16x32_bf16 v[118:121], v[168:171], v[202:205], v[118:121]
	v_mfma_f32_16x16x32_bf16 v[110:113], v[172:175], v[180:183], v[110:113]
	v_mfma_f32_16x16x32_bf16 v[110:113], v[176:179], v[202:205], v[110:113]
	v_mfma_f32_16x16x32_bf16 v[114:117], v[130:133], v[206:209], v[114:117]
	v_mfma_f32_16x16x32_bf16 v[114:117], v[134:137], v[210:213], v[114:117]
	v_mfma_f32_16x16x32_bf16 v[106:109], v[138:141], v[206:209], v[106:109]
	v_mfma_f32_16x16x32_bf16 v[106:109], v[142:145], v[210:213], v[106:109]
	v_mfma_f32_16x16x32_bf16 v[102:105], v[146:149], v[206:209], v[102:105]
	v_mfma_f32_16x16x32_bf16 v[102:105], v[168:171], v[210:213], v[102:105]
	v_mfma_f32_16x16x32_bf16 v[94:97], v[172:175], v[206:209], v[94:97]
	v_mfma_f32_16x16x32_bf16 v[94:97], v[176:179], v[210:213], v[94:97]
	s_setprio 0
	s_setprio 1
	v_mfma_f32_16x16x32_bf16 v[98:101], v[130:133], v[214:217], v[98:101]
	v_mfma_f32_16x16x32_bf16 v[98:101], v[134:137], v[226:229], v[98:101]
	v_mfma_f32_16x16x32_bf16 v[90:93], v[138:141], v[214:217], v[90:93]
	v_mfma_f32_16x16x32_bf16 v[90:93], v[142:145], v[226:229], v[90:93]
	v_mfma_f32_16x16x32_bf16 v[86:89], v[146:149], v[214:217], v[86:89]
	v_mfma_f32_16x16x32_bf16 v[86:89], v[168:171], v[226:229], v[86:89]
	v_mfma_f32_16x16x32_bf16 v[78:81], v[172:175], v[214:217], v[78:81]
	v_mfma_f32_16x16x32_bf16 v[78:81], v[176:179], v[226:229], v[78:81]
	v_mfma_f32_16x16x32_bf16 v[82:85], v[130:133], v[230:233], v[82:85]
	v_mfma_f32_16x16x32_bf16 v[82:85], v[134:137], v[234:237], v[82:85]
	v_mfma_f32_16x16x32_bf16 v[74:77], v[138:141], v[230:233], v[74:77]
	v_mfma_f32_16x16x32_bf16 v[74:77], v[142:145], v[234:237], v[74:77]
	v_mfma_f32_16x16x32_bf16 v[70:73], v[146:149], v[230:233], v[70:73]
	v_mfma_f32_16x16x32_bf16 v[70:73], v[168:171], v[234:237], v[70:73]
	v_mfma_f32_16x16x32_bf16 v[66:69], v[172:175], v[230:233], v[66:69]
	v_mfma_f32_16x16x32_bf16 v[66:69], v[176:179], v[234:237], v[66:69]
	s_setprio 0
	s_barrier
	s_add_i32 s52, s70, s81
	v_lshl_add_u64 v[196:197], v[196:197], 0, s[38:39]
	s_mov_b32 m0, s52
	ds_read_b128 v[180:183], v190 offset:49152
	ds_read_b128 v[202:205], v190 offset:50176
	ds_read_b128 v[206:209], v190 offset:51200
	ds_read_b128 v[210:213], v190 offset:52224
	ds_read_b128 v[214:217], v190 offset:53248
	ds_read_b128 v[226:229], v190 offset:54272
	ds_read_b128 v[230:233], v190 offset:55296
	ds_read_b128 v[234:237], v190 offset:56320
	global_load_lds_dwordx4 v[196:197], off
	s_add_i32 m0, s52, 0x2000
	s_add_u32 s10, s10, 0x80080
	v_lshl_add_u64 v[196:197], v[238:239], 0, s[38:39]
	s_addc_u32 s11, s11, 0
	s_add_i32 s52, s71, s81
	global_load_lds_dwordx4 v[196:197], off
	v_lshl_add_u64 v[196:197], s[10:11], 0, v[152:153]
	s_mov_b32 m0, s52
	s_nop 0
	global_load_lds_dwordx4 v[196:197], off
	v_lshl_add_u64 v[196:197], s[10:11], 0, v[156:157]
	s_add_i32 m0, s52, 0x2000
	s_nop 0
	global_load_lds_dwordx4 v[196:197], off
	v_lshl_add_u64 v[196:197], v[240:241], 0, s[38:39]
	s_mov_b32 m0, s90
	s_nop 0
	global_load_lds_dwordx4 v[196:197], off
	v_lshl_add_u64 v[196:197], v[242:243], 0, s[38:39]
	s_mov_b32 m0, s91
	s_nop 0
	global_load_lds_dwordx4 v[196:197], off
	s_waitcnt vmcnt(8)
	s_waitcnt lgkmcnt(0)
	s_barrier
	s_setprio 1
	s_waitcnt lgkmcnt(0)
	v_mfma_f32_16x16x32_bf16 v[62:65], v[130:133], v[180:183], v[62:65]
	v_mfma_f32_16x16x32_bf16 v[62:65], v[134:137], v[202:205], v[62:65]
	v_mfma_f32_16x16x32_bf16 v[58:61], v[138:141], v[180:183], v[58:61]
	v_mfma_f32_16x16x32_bf16 v[58:61], v[142:145], v[202:205], v[58:61]
	v_mfma_f32_16x16x32_bf16 v[50:53], v[146:149], v[180:183], v[50:53]
	v_mfma_f32_16x16x32_bf16 v[50:53], v[168:171], v[202:205], v[50:53]
	v_mfma_f32_16x16x32_bf16 v[42:45], v[172:175], v[180:183], v[42:45]
	v_mfma_f32_16x16x32_bf16 v[42:45], v[176:179], v[202:205], v[42:45]
	v_mfma_f32_16x16x32_bf16 v[54:57], v[130:133], v[206:209], v[54:57]
	v_mfma_f32_16x16x32_bf16 v[54:57], v[134:137], v[210:213], v[54:57]
	v_mfma_f32_16x16x32_bf16 v[46:49], v[138:141], v[206:209], v[46:49]
	v_mfma_f32_16x16x32_bf16 v[46:49], v[142:145], v[210:213], v[46:49]
	v_mfma_f32_16x16x32_bf16 v[34:37], v[146:149], v[206:209], v[34:37]
	v_mfma_f32_16x16x32_bf16 v[34:37], v[168:171], v[210:213], v[34:37]
	v_mfma_f32_16x16x32_bf16 v[26:29], v[172:175], v[206:209], v[26:29]
	v_mfma_f32_16x16x32_bf16 v[26:29], v[176:179], v[210:213], v[26:29]
	s_setprio 0
	s_setprio 1
	v_mfma_f32_16x16x32_bf16 v[38:41], v[130:133], v[214:217], v[38:41]
	v_mfma_f32_16x16x32_bf16 v[38:41], v[134:137], v[226:229], v[38:41]
	v_mfma_f32_16x16x32_bf16 v[30:33], v[138:141], v[214:217], v[30:33]
	v_mfma_f32_16x16x32_bf16 v[30:33], v[142:145], v[226:229], v[30:33]
	v_mfma_f32_16x16x32_bf16 v[18:21], v[146:149], v[214:217], v[18:21]
	v_mfma_f32_16x16x32_bf16 v[18:21], v[168:171], v[226:229], v[18:21]
	v_mfma_f32_16x16x32_bf16 v[10:13], v[172:175], v[214:217], v[10:13]
	v_mfma_f32_16x16x32_bf16 v[10:13], v[176:179], v[226:229], v[10:13]
	v_mfma_f32_16x16x32_bf16 v[22:25], v[130:133], v[230:233], v[22:25]
	v_mfma_f32_16x16x32_bf16 v[22:25], v[134:137], v[234:237], v[22:25]
	v_mfma_f32_16x16x32_bf16 v[14:17], v[138:141], v[230:233], v[14:17]
	v_mfma_f32_16x16x32_bf16 v[14:17], v[142:145], v[234:237], v[14:17]
	v_mfma_f32_16x16x32_bf16 v[6:9], v[146:149], v[230:233], v[6:9]
	v_mfma_f32_16x16x32_bf16 v[6:9], v[168:171], v[234:237], v[6:9]
	v_mfma_f32_16x16x32_bf16 v[2:5], v[172:175], v[230:233], v[2:5]
	v_mfma_f32_16x16x32_bf16 v[2:5], v[176:179], v[234:237], v[2:5]
	s_setprio 0
	s_barrier
	s_add_i32 s69, s69, 2
	s_add_u32 s61, s61, 0x100
	s_addc_u32 s68, s68, 0
	s_add_u32 s8, s8, 0x100
	s_addc_u32 s9, s9, 0
	s_cmp_gt_u32 s69, 29
	s_cbranch_scc0 .LBB0_531
	v_mov_b32_e32 v132, v185
	v_mov_b32_e32 v130, v186
	s_cmp_lt_i32 s54, 12
	v_mov_b32_e32 v131, s56
	v_add_u32_e32 v196, s89, v132
	s_cselect_b64 s[8:9], -1, 0
	s_and_saveexec_b64 s[10:11], s[8:9]
	s_xor_b64 s[66:67], exec, s[10:11]
	s_cbranch_execz .LBB0_665
	v_lshlrev_b32_e64 v133, 2, s54
	v_and_or_b32 v179, v133, 12, s88
	v_add_u32_e64 v133, s56, -16
	v_lshrrev_b32_e32 v133, 4, v133
	v_cmp_lt_i32_e64 vcc, s56, 16
	v_cmp_gt_i32_e64 s[8:9], s54, 7
	s_nop 0
	v_cndmask_b32_e32 v131, v133, v131, vcc
	v_lshlrev_b32_e64 v133, 8, s56
	v_and_b32_e32 v133, 0xf00, v133
	v_cndmask_b32_e64 v140, v133, 0, vcc
	v_lshl_or_b32 v138, v131, 4, v179
	s_and_saveexec_b64 s[10:11], s[8:9]
	s_xor_b64 s[68:69], exec, s[10:11]
	s_cbranch_execz .LBB0_567
	v_lshlrev_b32_e32 v135, 14, v138
	v_lshlrev_b32_e32 v134, 3, v130
	v_lshl_add_u32 v141, v196, 6, v135
	s_and_saveexec_b64 s[8:9], vcc
	s_cbranch_execz .LBB0_536
	v_add_u32_e32 v158, v141, v134
	v_lshl_add_u64 v[130:131], v[158:159], 2, s[18:19]
	global_store_dwordx4 v[130:131], v[126:129], off
	global_store_dwordx4 v[130:131], v[122:125], off offset:16

.LBB0_1158:
	ds_read_b128 v[150:153], v227
	ds_read_b128 v[154:157], v227 offset:1024
	ds_read_b128 v[158:161], v227 offset:2048
	ds_read_b128 v[162:165], v227 offset:3072
	ds_read_b128 v[134:137], v228
	ds_read_b128 v[138:141], v228 offset:1024
	ds_read_b128 v[142:145], v228 offset:2048
	ds_read_b128 v[146:149], v228 offset:3072
	s_mov_b64 s[6:7], s[52:53]
	s_add_u32 s52, s6, 0x100
	s_addc_u32 s53, s7, 0
	s_cmp_eq_u32 s83, 28
	s_cselect_b32 s59, s27, s53
	s_cselect_b32 s58, s34, s52
	s_cselect_b32 s57, s25, s82
	s_cselect_b32 s56, s35, s39
	v_lshl_add_u64 v[4:5], s[6:7], 0, v[208:209]
	s_add_i32 m0, s61, 0xc000
	s_waitcnt lgkmcnt(0)
	ds_read_b128 v[166:169], v229
	ds_read_b128 v[170:173], v229 offset:1024
	ds_read_b128 v[174:177], v229 offset:2048
	ds_read_b128 v[178:181], v229 offset:3072
	ds_read_b128 v[182:185], v229 offset:4096
	ds_read_b128 v[186:189], v229 offset:5120
	ds_read_b128 v[190:193], v229 offset:6144
	ds_read_b128 v[194:197], v229 offset:7168
	global_load_lds_dwordx4 v[4:5], off
	v_lshl_add_u64 v[4:5], s[6:7], 0, v[206:207]
	s_add_i32 m0, s61, 0xe000
	s_nop 0
	global_load_lds_dwordx4 v[4:5], off
	s_waitcnt vmcnt(8)
	s_waitcnt lgkmcnt(0)
	s_barrier
	s_setprio 1
	s_waitcnt lgkmcnt(0)
	v_mfma_f32_16x16x32_bf16 v[130:133], v[150:153], v[166:169], v[130:133]
	v_mfma_f32_16x16x32_bf16 v[130:133], v[154:157], v[170:173], v[130:133]
	v_mfma_f32_16x16x32_bf16 v[126:129], v[158:161], v[166:169], v[126:129]
	v_mfma_f32_16x16x32_bf16 v[126:129], v[162:165], v[170:173], v[126:129]
	v_mfma_f32_16x16x32_bf16 v[110:113], v[134:137], v[166:169], v[110:113]
	v_mfma_f32_16x16x32_bf16 v[110:113], v[138:141], v[170:173], v[110:113]
	v_mfma_f32_16x16x32_bf16 v[102:105], v[142:145], v[166:169], v[102:105]
	v_mfma_f32_16x16x32_bf16 v[102:105], v[146:149], v[170:173], v[102:105]
	v_mfma_f32_16x16x32_bf16 v[122:125], v[150:153], v[174:177], v[122:125]
	v_mfma_f32_16x16x32_bf16 v[122:125], v[154:157], v[178:181], v[122:125]
	v_mfma_f32_16x16x32_bf16 v[118:121], v[158:161], v[174:177], v[118:121]
	v_mfma_f32_16x16x32_bf16 v[118:121], v[162:165], v[178:181], v[118:121]
	v_mfma_f32_16x16x32_bf16 v[94:97], v[134:137], v[174:177], v[94:97]
	v_mfma_f32_16x16x32_bf16 v[94:97], v[138:141], v[178:181], v[94:97]
	v_mfma_f32_16x16x32_bf16 v[90:93], v[142:145], v[174:177], v[90:93]
	v_mfma_f32_16x16x32_bf16 v[90:93], v[146:149], v[178:181], v[90:93]
	s_setprio 0
	s_setprio 1
	v_mfma_f32_16x16x32_bf16 v[114:117], v[150:153], v[182:185], v[114:117]
	v_mfma_f32_16x16x32_bf16 v[114:117], v[154:157], v[186:189], v[114:117]
	v_mfma_f32_16x16x32_bf16 v[106:109], v[158:161], v[182:185], v[106:109]
	v_mfma_f32_16x16x32_bf16 v[106:109], v[162:165], v[186:189], v[106:109]
	v_mfma_f32_16x16x32_bf16 v[82:85], v[134:137], v[182:185], v[82:85]
	v_mfma_f32_16x16x32_bf16 v[82:85], v[138:141], v[186:189], v[82:85]
	v_mfma_f32_16x16x32_bf16 v[78:81], v[142:145], v[182:185], v[78:81]
	v_mfma_f32_16x16x32_bf16 v[78:81], v[146:149], v[186:189], v[78:81]
	v_mfma_f32_16x16x32_bf16 v[98:101], v[150:153], v[190:193], v[98:101]
	v_mfma_f32_16x16x32_bf16 v[98:101], v[154:157], v[194:197], v[98:101]
	v_mfma_f32_16x16x32_bf16 v[86:89], v[158:161], v[190:193], v[86:89]
	v_mfma_f32_16x16x32_bf16 v[86:89], v[162:165], v[194:197], v[86:89]
	v_mfma_f32_16x16x32_bf16 v[74:77], v[134:137], v[190:193], v[74:77]
	v_mfma_f32_16x16x32_bf16 v[74:77], v[138:141], v[194:197], v[74:77]
	v_mfma_f32_16x16x32_bf16 v[70:73], v[142:145], v[190:193], v[70:73]
	v_mfma_f32_16x16x32_bf16 v[70:73], v[146:149], v[194:197], v[70:73]
	s_setprio 0
	s_barrier
	s_add_i32 s6, s77, s60
	v_lshl_add_u64 v[4:5], s[56:57], 0, v[202:203]
	s_mov_b32 m0, s6
	ds_read_b128 v[190:193], v229 offset:16384
	ds_read_b128 v[194:197], v229 offset:17408
	ds_read_b128 v[182:185], v229 offset:18432
	ds_read_b128 v[186:189], v229 offset:19456
	ds_read_b128 v[174:177], v229 offset:20480
	ds_read_b128 v[178:181], v229 offset:21504
	ds_read_b128 v[166:169], v229 offset:22528
	ds_read_b128 v[170:173], v229 offset:23552
	global_load_lds_dwordx4 v[4:5], off
	s_add_i32 m0, s6, 0x2000
	s_add_u32 s6, s56, 0x80000
	v_lshl_add_u64 v[212:213], s[56:57], 0, v[204:205]
	s_addc_u32 s7, s57, 0
	s_add_i32 s84, s78, s60
	global_load_lds_dwordx4 v[212:213], off
	v_lshl_add_u64 v[214:215], s[6:7], 0, v[202:203]
	s_mov_b32 m0, s84
	v_lshl_add_u64 v[216:217], s[58:59], 0, v[204:205]
	global_load_lds_dwordx4 v[214:215], off
	v_lshl_add_u64 v[214:215], s[6:7], 0, v[204:205]
	s_add_i32 m0, s84, 0x2000
	v_cmp_ne_u32_e64 s[6:7], 1, v230
	global_load_lds_dwordx4 v[214:215], off
	v_lshl_add_u64 v[214:215], s[58:59], 0, v[202:203]
	s_mov_b32 m0, s61
	s_andn2_b64 vcc, exec, s[54:55]
	global_load_lds_dwordx4 v[214:215], off
	s_mov_b32 m0, s62
	s_nop 0
	global_load_lds_dwordx4 v[216:217], off
	s_waitcnt vmcnt(8)
	s_waitcnt lgkmcnt(0)
	s_barrier
	s_cbranch_vccnz .LBB0_1160
	s_setprio 1
	s_waitcnt lgkmcnt(0)
	v_mfma_f32_16x16x32_bf16 v[66:69], v[150:153], v[190:193], v[66:69]
	v_mfma_f32_16x16x32_bf16 v[66:69], v[154:157], v[194:197], v[66:69]
	v_mfma_f32_16x16x32_bf16 v[62:65], v[158:161], v[190:193], v[62:65]
	v_mfma_f32_16x16x32_bf16 v[62:65], v[162:165], v[194:197], v[62:65]
	v_mfma_f32_16x16x32_bf16 v[54:57], v[134:137], v[190:193], v[54:57]
	v_mfma_f32_16x16x32_bf16 v[54:57], v[138:141], v[194:197], v[54:57]
	v_mfma_f32_16x16x32_bf16 v[46:49], v[142:145], v[190:193], v[46:49]
	v_mfma_f32_16x16x32_bf16 v[46:49], v[146:149], v[194:197], v[46:49]
	v_mfma_f32_16x16x32_bf16 v[58:61], v[150:153], v[182:185], v[58:61]
	v_mfma_f32_16x16x32_bf16 v[58:61], v[154:157], v[186:189], v[58:61]
	v_mfma_f32_16x16x32_bf16 v[50:53], v[158:161], v[182:185], v[50:53]
	v_mfma_f32_16x16x32_bf16 v[50:53], v[162:165], v[186:189], v[50:53]
	v_mfma_f32_16x16x32_bf16 v[38:41], v[134:137], v[182:185], v[38:41]
	v_mfma_f32_16x16x32_bf16 v[38:41], v[138:141], v[186:189], v[38:41]
	v_mfma_f32_16x16x32_bf16 v[30:33], v[142:145], v[182:185], v[30:33]
	v_mfma_f32_16x16x32_bf16 v[30:33], v[146:149], v[186:189], v[30:33]
	s_setprio 0
	s_setprio 1
	v_mfma_f32_16x16x32_bf16 v[42:45], v[150:153], v[174:177], v[42:45]
	v_mfma_f32_16x16x32_bf16 v[42:45], v[154:157], v[178:181], v[42:45]
	v_mfma_f32_16x16x32_bf16 v[34:37], v[158:161], v[174:177], v[34:37]
	v_mfma_f32_16x16x32_bf16 v[34:37], v[162:165], v[178:181], v[34:37]
	v_mfma_f32_16x16x32_bf16 v[26:29], v[134:137], v[174:177], v[26:29]
	v_mfma_f32_16x16x32_bf16 v[26:29], v[138:141], v[178:181], v[26:29]
	v_mfma_f32_16x16x32_bf16 v[18:21], v[142:145], v[174:177], v[18:21]
	v_mfma_f32_16x16x32_bf16 v[18:21], v[146:149], v[178:181], v[18:21]
	v_mfma_f32_16x16x32_bf16 v[22:25], v[150:153], v[166:169], v[22:25]
	v_mfma_f32_16x16x32_bf16 v[22:25], v[154:157], v[170:173], v[22:25]
	v_mfma_f32_16x16x32_bf16 v[14:17], v[158:161], v[166:169], v[14:17]
	v_mfma_f32_16x16x32_bf16 v[14:17], v[162:165], v[170:173], v[14:17]
	v_mfma_f32_16x16x32_bf16 v[10:13], v[134:137], v[166:169], v[10:13]
	v_mfma_f32_16x16x32_bf16 v[10:13], v[138:141], v[170:173], v[10:13]
	v_mfma_f32_16x16x32_bf16 v[6:9], v[142:145], v[166:169], v[6:9]
	v_mfma_f32_16x16x32_bf16 v[6:9], v[146:149], v[170:173], v[6:9]
	s_setprio 0
.LBB0_1160:
	s_barrier
	s_add_i32 s84, 16, 0x18000
	v_add_u32_e32 v2, s84, v226
	s_add_i32 s85, 16, 0x1c000
	ds_read_b128 v[150:153], v2
	ds_read_b128 v[154:157], v2 offset:1024
	ds_read_b128 v[158:161], v2 offset:2048
	ds_read_b128 v[162:165], v2 offset:3072
	v_add_u32_e32 v2, s85, v226
	ds_read_b128 v[134:137], v2
	ds_read_b128 v[138:141], v2 offset:1024
	ds_read_b128 v[142:145], v2 offset:2048
	ds_read_b128 v[146:149], v2 offset:3072
	s_add_u32 s58, s58, 0x80000
	s_addc_u32 s59, s59, 0
	s_mov_b32 m0, s63
	v_lshl_add_u64 v[232:233], s[58:59], 0, v[202:203]
	s_waitcnt lgkmcnt(0)
	ds_read_b128 v[166:169], v229 offset:32768
	ds_read_b128 v[170:173], v229 offset:33792
	ds_read_b128 v[174:177], v229 offset:34816
	ds_read_b128 v[178:181], v229 offset:35840
	ds_read_b128 v[182:185], v229 offset:36864
	ds_read_b128 v[186:189], v229 offset:37888
	ds_read_b128 v[190:193], v229 offset:38912
	ds_read_b128 v[194:197], v229 offset:39936
	global_load_lds_dwordx4 v[232:233], off
	v_lshl_add_u64 v[232:233], s[58:59], 0, v[204:205]
	s_mov_b32 m0, s64
	s_nop 0
	global_load_lds_dwordx4 v[232:233], off
	s_waitcnt vmcnt(8)
	s_waitcnt lgkmcnt(0)
	s_barrier
	s_setprio 1
	s_waitcnt lgkmcnt(0)
	v_mfma_f32_16x16x32_bf16 v[130:133], v[150:153], v[166:169], v[130:133]
	v_mfma_f32_16x16x32_bf16 v[130:133], v[154:157], v[170:173], v[130:133]
	v_mfma_f32_16x16x32_bf16 v[126:129], v[158:161], v[166:169], v[126:129]
	v_mfma_f32_16x16x32_bf16 v[126:129], v[162:165], v[170:173], v[126:129]
	v_mfma_f32_16x16x32_bf16 v[110:113], v[134:137], v[166:169], v[110:113]
	v_mfma_f32_16x16x32_bf16 v[110:113], v[138:141], v[170:173], v[110:113]
	v_mfma_f32_16x16x32_bf16 v[102:105], v[142:145], v[166:169], v[102:105]
	v_mfma_f32_16x16x32_bf16 v[102:105], v[146:149], v[170:173], v[102:105]
	v_mfma_f32_16x16x32_bf16 v[122:125], v[150:153], v[174:177], v[122:125]
	v_mfma_f32_16x16x32_bf16 v[122:125], v[154:157], v[178:181], v[122:125]
	v_mfma_f32_16x16x32_bf16 v[118:121], v[158:161], v[174:177], v[118:121]
	v_mfma_f32_16x16x32_bf16 v[118:121], v[162:165], v[178:181], v[118:121]
	v_mfma_f32_16x16x32_bf16 v[94:97], v[134:137], v[174:177], v[94:97]
	v_mfma_f32_16x16x32_bf16 v[94:97], v[138:141], v[178:181], v[94:97]
	v_mfma_f32_16x16x32_bf16 v[90:93], v[142:145], v[174:177], v[90:93]
	v_mfma_f32_16x16x32_bf16 v[90:93], v[146:149], v[178:181], v[90:93]
	s_setprio 0
	s_setprio 1
	v_mfma_f32_16x16x32_bf16 v[114:117], v[150:153], v[182:185], v[114:117]
	v_mfma_f32_16x16x32_bf16 v[114:117], v[154:157], v[186:189], v[114:117]
	v_mfma_f32_16x16x32_bf16 v[106:109], v[158:161], v[182:185], v[106:109]
	v_mfma_f32_16x16x32_bf16 v[106:109], v[162:165], v[186:189], v[106:109]
	v_mfma_f32_16x16x32_bf16 v[82:85], v[134:137], v[182:185], v[82:85]
	v_mfma_f32_16x16x32_bf16 v[82:85], v[138:141], v[186:189], v[82:85]
	v_mfma_f32_16x16x32_bf16 v[78:81], v[142:145], v[182:185], v[78:81]
	v_mfma_f32_16x16x32_bf16 v[78:81], v[146:149], v[186:189], v[78:81]
	v_mfma_f32_16x16x32_bf16 v[98:101], v[150:153], v[190:193], v[98:101]
	v_mfma_f32_16x16x32_bf16 v[98:101], v[154:157], v[194:197], v[98:101]
	v_mfma_f32_16x16x32_bf16 v[86:89], v[158:161], v[190:193], v[86:89]
	v_mfma_f32_16x16x32_bf16 v[86:89], v[162:165], v[194:197], v[86:89]
	v_mfma_f32_16x16x32_bf16 v[74:77], v[134:137], v[190:193], v[74:77]
	v_mfma_f32_16x16x32_bf16 v[74:77], v[138:141], v[194:197], v[74:77]
	v_mfma_f32_16x16x32_bf16 v[70:73], v[142:145], v[190:193], v[70:73]
	v_mfma_f32_16x16x32_bf16 v[70:73], v[146:149], v[194:197], v[70:73]
	s_setprio 0
	s_barrier
	s_add_i32 s58, s84, s60
	v_lshl_add_u64 v[4:5], v[4:5], 0, s[10:11]
	s_mov_b32 m0, s58
	ds_read_b128 v[190:193], v229 offset:49152
	ds_read_b128 v[194:197], v229 offset:50176
	ds_read_b128 v[182:185], v229 offset:51200
	ds_read_b128 v[186:189], v229 offset:52224
	ds_read_b128 v[174:177], v229 offset:53248
	ds_read_b128 v[178:181], v229 offset:54272
	ds_read_b128 v[166:169], v229 offset:55296
	ds_read_b128 v[170:173], v229 offset:56320
	global_load_lds_dwordx4 v[4:5], off
	s_add_i32 m0, s58, 0x2000
	s_add_u32 s56, s56, 0x80080
	v_lshl_add_u64 v[4:5], v[212:213], 0, s[10:11]
	s_addc_u32 s57, s57, 0
	s_add_i32 s58, s85, s60
	global_load_lds_dwordx4 v[4:5], off
	v_lshl_add_u64 v[4:5], s[56:57], 0, v[202:203]
	s_mov_b32 m0, s58
	s_and_b64 vcc, exec, s[6:7]
	global_load_lds_dwordx4 v[4:5], off
	v_lshl_add_u64 v[4:5], s[56:57], 0, v[204:205]
	s_add_i32 m0, s58, 0x2000
	s_nop 0
	global_load_lds_dwordx4 v[4:5], off
	v_lshl_add_u64 v[4:5], v[214:215], 0, s[10:11]
	s_mov_b32 m0, s70
	s_nop 0
	global_load_lds_dwordx4 v[4:5], off
	v_lshl_add_u64 v[4:5], v[216:217], 0, s[10:11]
	s_mov_b32 m0, s71
	s_nop 0
	global_load_lds_dwordx4 v[4:5], off
	s_waitcnt vmcnt(8)
	s_waitcnt lgkmcnt(0)
	s_barrier
	s_cbranch_vccnz .LBB0_1157
	s_setprio 1
	s_waitcnt lgkmcnt(0)
	v_mfma_f32_16x16x32_bf16 v[66:69], v[150:153], v[190:193], v[66:69]
	v_mfma_f32_16x16x32_bf16 v[66:69], v[154:157], v[194:197], v[66:69]
	v_mfma_f32_16x16x32_bf16 v[62:65], v[158:161], v[190:193], v[62:65]
	v_mfma_f32_16x16x32_bf16 v[62:65], v[162:165], v[194:197], v[62:65]
	v_mfma_f32_16x16x32_bf16 v[54:57], v[134:137], v[190:193], v[54:57]
	v_mfma_f32_16x16x32_bf16 v[54:57], v[138:141], v[194:197], v[54:57]
	v_mfma_f32_16x16x32_bf16 v[46:49], v[142:145], v[190:193], v[46:49]
	v_mfma_f32_16x16x32_bf16 v[46:49], v[146:149], v[194:197], v[46:49]
	v_mfma_f32_16x16x32_bf16 v[58:61], v[150:153], v[182:185], v[58:61]
	v_mfma_f32_16x16x32_bf16 v[58:61], v[154:157], v[186:189], v[58:61]
	v_mfma_f32_16x16x32_bf16 v[50:53], v[158:161], v[182:185], v[50:53]
	v_mfma_f32_16x16x32_bf16 v[50:53], v[162:165], v[186:189], v[50:53]
	v_mfma_f32_16x16x32_bf16 v[38:41], v[134:137], v[182:185], v[38:41]
	v_mfma_f32_16x16x32_bf16 v[38:41], v[138:141], v[186:189], v[38:41]
	v_mfma_f32_16x16x32_bf16 v[30:33], v[142:145], v[182:185], v[30:33]
	v_mfma_f32_16x16x32_bf16 v[30:33], v[146:149], v[186:189], v[30:33]
	s_setprio 0
	s_setprio 1
	v_mfma_f32_16x16x32_bf16 v[42:45], v[150:153], v[174:177], v[42:45]
	v_mfma_f32_16x16x32_bf16 v[42:45], v[154:157], v[178:181], v[42:45]
	v_mfma_f32_16x16x32_bf16 v[34:37], v[158:161], v[174:177], v[34:37]
	v_mfma_f32_16x16x32_bf16 v[34:37], v[162:165], v[178:181], v[34:37]
	v_mfma_f32_16x16x32_bf16 v[26:29], v[134:137], v[174:177], v[26:29]
	v_mfma_f32_16x16x32_bf16 v[26:29], v[138:141], v[178:181], v[26:29]
	v_mfma_f32_16x16x32_bf16 v[18:21], v[142:145], v[174:177], v[18:21]
	v_mfma_f32_16x16x32_bf16 v[18:21], v[146:149], v[178:181], v[18:21]
	v_mfma_f32_16x16x32_bf16 v[22:25], v[150:153], v[166:169], v[22:25]
	v_mfma_f32_16x16x32_bf16 v[22:25], v[154:157], v[170:173], v[22:25]
	v_mfma_f32_16x16x32_bf16 v[14:17], v[158:161], v[166:169], v[14:17]
	v_mfma_f32_16x16x32_bf16 v[14:17], v[162:165], v[170:173], v[14:17]
	v_mfma_f32_16x16x32_bf16 v[10:13], v[134:137], v[166:169], v[10:13]
	v_mfma_f32_16x16x32_bf16 v[10:13], v[138:141], v[170:173], v[10:13]
	v_mfma_f32_16x16x32_bf16 v[4:7], v[142:145], v[166:169], v[6:9]
	v_mfma_f32_16x16x32_bf16 v[6:9], v[146:149], v[170:173], v[4:7]
	s_setprio 0
	s_branch .LBB0_1157

.LBB0_1297:
	ds_read_b128 v[154:157], v150
	ds_read_b128 v[158:161], v150 offset:1024
	ds_read_b128 v[162:165], v150 offset:2048
	ds_read_b128 v[166:169], v150 offset:3072
	ds_read_b128 v[170:173], v151
	ds_read_b128 v[174:177], v151 offset:1024
	ds_read_b128 v[178:181], v151 offset:2048
	ds_read_b128 v[182:185], v151 offset:3072
	s_add_u32 s36, s30, 0xfff80080
	s_addc_u32 s37, s31, -1
	s_cmp_eq_u32 s66, 28
	s_cselect_b32 s39, s23, s37
	s_cselect_b32 s38, s34, s36
	s_cselect_b32 s37, s21, s65
	s_cselect_b32 s36, s35, s64
	v_lshl_add_u64 v[220:221], s[30:31], 0, v[142:143]
	s_add_i32 m0, s29, 0xc000
	ds_read_b128 v[186:189], v152
	ds_read_b128 v[190:193], v152 offset:1024
	ds_read_b128 v[194:197], v152 offset:2048
	ds_read_b128 v[198:201], v152 offset:3072
	ds_read_b128 v[202:205], v152 offset:4096
	ds_read_b128 v[206:209], v152 offset:5120
	ds_read_b128 v[210:213], v152 offset:6144
	ds_read_b128 v[214:217], v152 offset:7168
	global_load_lds_dwordx4 v[220:221], off
	v_lshl_add_u64 v[220:221], s[30:31], 0, v[140:141]
	s_add_i32 m0, s29, 0xe000
	s_nop 0
	global_load_lds_dwordx4 v[220:221], off
	s_waitcnt vmcnt(8)
	s_waitcnt lgkmcnt(0)
	s_barrier
	s_setprio 1
	s_waitcnt lgkmcnt(0)
	v_mfma_f32_16x16x32_bf16 v[126:129], v[154:157], v[186:189], v[126:129]
	v_mfma_f32_16x16x32_bf16 v[126:129], v[158:161], v[190:193], v[126:129]
	v_mfma_f32_16x16x32_bf16 v[122:125], v[162:165], v[186:189], v[122:125]
	v_mfma_f32_16x16x32_bf16 v[122:125], v[166:169], v[190:193], v[122:125]
	v_mfma_f32_16x16x32_bf16 v[118:121], v[170:173], v[186:189], v[118:121]
	v_mfma_f32_16x16x32_bf16 v[118:121], v[174:177], v[190:193], v[118:121]
	v_mfma_f32_16x16x32_bf16 v[114:117], v[178:181], v[186:189], v[114:117]
	v_mfma_f32_16x16x32_bf16 v[114:117], v[182:185], v[190:193], v[114:117]
	v_mfma_f32_16x16x32_bf16 v[110:113], v[154:157], v[194:197], v[110:113]
	v_mfma_f32_16x16x32_bf16 v[110:113], v[158:161], v[198:201], v[110:113]
	v_mfma_f32_16x16x32_bf16 v[106:109], v[162:165], v[194:197], v[106:109]
	v_mfma_f32_16x16x32_bf16 v[106:109], v[166:169], v[198:201], v[106:109]
	v_mfma_f32_16x16x32_bf16 v[102:105], v[170:173], v[194:197], v[102:105]
	v_mfma_f32_16x16x32_bf16 v[102:105], v[174:177], v[198:201], v[102:105]
	v_mfma_f32_16x16x32_bf16 v[98:101], v[178:181], v[194:197], v[98:101]
	v_mfma_f32_16x16x32_bf16 v[98:101], v[182:185], v[198:201], v[98:101]
	s_setprio 0
	s_setprio 1
	v_mfma_f32_16x16x32_bf16 v[94:97], v[154:157], v[202:205], v[94:97]
	v_mfma_f32_16x16x32_bf16 v[94:97], v[158:161], v[206:209], v[94:97]
	v_mfma_f32_16x16x32_bf16 v[90:93], v[162:165], v[202:205], v[90:93]
	v_mfma_f32_16x16x32_bf16 v[90:93], v[166:169], v[206:209], v[90:93]
	v_mfma_f32_16x16x32_bf16 v[86:89], v[170:173], v[202:205], v[86:89]
	v_mfma_f32_16x16x32_bf16 v[86:89], v[174:177], v[206:209], v[86:89]
	v_mfma_f32_16x16x32_bf16 v[82:85], v[178:181], v[202:205], v[82:85]
	v_mfma_f32_16x16x32_bf16 v[82:85], v[182:185], v[206:209], v[82:85]
	v_mfma_f32_16x16x32_bf16 v[78:81], v[154:157], v[210:213], v[78:81]
	v_mfma_f32_16x16x32_bf16 v[78:81], v[158:161], v[214:217], v[78:81]
	v_mfma_f32_16x16x32_bf16 v[74:77], v[162:165], v[210:213], v[74:77]
	v_mfma_f32_16x16x32_bf16 v[74:77], v[166:169], v[214:217], v[74:77]
	v_mfma_f32_16x16x32_bf16 v[70:73], v[170:173], v[210:213], v[70:73]
	v_mfma_f32_16x16x32_bf16 v[70:73], v[174:177], v[214:217], v[70:73]
	v_mfma_f32_16x16x32_bf16 v[66:69], v[178:181], v[210:213], v[66:69]
	v_mfma_f32_16x16x32_bf16 v[66:69], v[182:185], v[214:217], v[66:69]
	s_setprio 0
	s_barrier
	s_add_i32 s67, s60, s48
	v_lshl_add_u64 v[220:221], s[36:37], 0, v[134:135]
	s_mov_b32 m0, s67
	ds_read_b128 v[186:189], v152 offset:16384
	ds_read_b128 v[190:193], v152 offset:17408
	ds_read_b128 v[194:197], v152 offset:18432
	ds_read_b128 v[198:201], v152 offset:19456
	ds_read_b128 v[202:205], v152 offset:20480
	ds_read_b128 v[206:209], v152 offset:21504
	ds_read_b128 v[210:213], v152 offset:22528
	ds_read_b128 v[214:217], v152 offset:23552
	global_load_lds_dwordx4 v[220:221], off
	s_add_i32 m0, s67, 0x2000
	s_add_u32 s68, s36, 0x80000
	v_lshl_add_u64 v[222:223], s[36:37], 0, v[130:131]
	s_addc_u32 s69, s37, 0
	s_add_i32 s67, s61, s48
	global_load_lds_dwordx4 v[222:223], off
	v_lshl_add_u64 v[224:225], s[68:69], 0, v[134:135]
	s_mov_b32 m0, s67
	v_lshl_add_u64 v[226:227], s[38:39], 0, v[132:133]
	global_load_lds_dwordx4 v[224:225], off
	v_lshl_add_u64 v[224:225], s[68:69], 0, v[130:131]
	s_add_i32 m0, s67, 0x2000
	s_nop 0
	global_load_lds_dwordx4 v[224:225], off
	v_lshl_add_u64 v[224:225], s[38:39], 0, v[136:137]
	s_mov_b32 m0, s29
	s_nop 0
	global_load_lds_dwordx4 v[224:225], off
	s_mov_b32 m0, s51
	s_nop 0
	global_load_lds_dwordx4 v[226:227], off
	s_waitcnt vmcnt(8)
	s_waitcnt lgkmcnt(0)
	s_barrier
	s_setprio 1
	s_waitcnt lgkmcnt(0)
	v_mfma_f32_16x16x32_bf16 v[62:65], v[154:157], v[186:189], v[62:65]
	v_mfma_f32_16x16x32_bf16 v[62:65], v[158:161], v[190:193], v[62:65]
	v_mfma_f32_16x16x32_bf16 v[58:61], v[162:165], v[186:189], v[58:61]
	v_mfma_f32_16x16x32_bf16 v[58:61], v[166:169], v[190:193], v[58:61]
	v_mfma_f32_16x16x32_bf16 v[54:57], v[170:173], v[186:189], v[54:57]
	v_mfma_f32_16x16x32_bf16 v[54:57], v[174:177], v[190:193], v[54:57]
	v_mfma_f32_16x16x32_bf16 v[50:53], v[178:181], v[186:189], v[50:53]
	v_mfma_f32_16x16x32_bf16 v[50:53], v[182:185], v[190:193], v[50:53]
	v_mfma_f32_16x16x32_bf16 v[46:49], v[154:157], v[194:197], v[46:49]
	v_mfma_f32_16x16x32_bf16 v[46:49], v[158:161], v[198:201], v[46:49]
	v_mfma_f32_16x16x32_bf16 v[42:45], v[162:165], v[194:197], v[42:45]
	v_mfma_f32_16x16x32_bf16 v[42:45], v[166:169], v[198:201], v[42:45]
	v_mfma_f32_16x16x32_bf16 v[38:41], v[170:173], v[194:197], v[38:41]
	v_mfma_f32_16x16x32_bf16 v[38:41], v[174:177], v[198:201], v[38:41]
	v_mfma_f32_16x16x32_bf16 v[34:37], v[178:181], v[194:197], v[34:37]
	v_mfma_f32_16x16x32_bf16 v[34:37], v[182:185], v[198:201], v[34:37]
	s_setprio 0
	s_setprio 1
	v_mfma_f32_16x16x32_bf16 v[30:33], v[154:157], v[202:205], v[30:33]
	v_mfma_f32_16x16x32_bf16 v[30:33], v[158:161], v[206:209], v[30:33]
	v_mfma_f32_16x16x32_bf16 v[26:29], v[162:165], v[202:205], v[26:29]
	v_mfma_f32_16x16x32_bf16 v[26:29], v[166:169], v[206:209], v[26:29]
	v_mfma_f32_16x16x32_bf16 v[22:25], v[170:173], v[202:205], v[22:25]
	v_mfma_f32_16x16x32_bf16 v[22:25], v[174:177], v[206:209], v[22:25]
	v_mfma_f32_16x16x32_bf16 v[18:21], v[178:181], v[202:205], v[18:21]
	v_mfma_f32_16x16x32_bf16 v[18:21], v[182:185], v[206:209], v[18:21]
	v_mfma_f32_16x16x32_bf16 v[14:17], v[154:157], v[210:213], v[14:17]
	v_mfma_f32_16x16x32_bf16 v[14:17], v[158:161], v[214:217], v[14:17]
	v_mfma_f32_16x16x32_bf16 v[10:13], v[162:165], v[210:213], v[10:13]
	v_mfma_f32_16x16x32_bf16 v[10:13], v[166:169], v[214:217], v[10:13]
	v_mfma_f32_16x16x32_bf16 v[6:9], v[170:173], v[210:213], v[6:9]
	v_mfma_f32_16x16x32_bf16 v[6:9], v[174:177], v[214:217], v[6:9]
	v_mfma_f32_16x16x32_bf16 v[2:5], v[178:181], v[210:213], v[2:5]
	v_mfma_f32_16x16x32_bf16 v[2:5], v[182:185], v[214:217], v[2:5]
	s_setprio 0
	s_barrier
	s_add_i32 s67, 16, 0x18000
	v_add_u32_e32 v138, s67, v149
	s_add_i32 s68, 16, 0x1c000
	ds_read_b128 v[154:157], v138
	ds_read_b128 v[158:161], v138 offset:1024
	ds_read_b128 v[162:165], v138 offset:2048
	ds_read_b128 v[166:169], v138 offset:3072
	v_add_u32_e32 v138, s68, v149
	ds_read_b128 v[170:173], v138
	ds_read_b128 v[174:177], v138 offset:1024
	ds_read_b128 v[178:181], v138 offset:2048
	ds_read_b128 v[182:185], v138 offset:3072
	s_add_u32 s38, s38, 0x80000
	s_addc_u32 s39, s39, 0
	s_mov_b32 m0, s52
	v_lshl_add_u64 v[228:229], s[38:39], 0, v[136:137]
	ds_read_b128 v[186:189], v152 offset:32768
	ds_read_b128 v[190:193], v152 offset:33792
	ds_read_b128 v[194:197], v152 offset:34816
	ds_read_b128 v[198:201], v152 offset:35840
	ds_read_b128 v[202:205], v152 offset:36864
	ds_read_b128 v[206:209], v152 offset:37888
	ds_read_b128 v[210:213], v152 offset:38912
	ds_read_b128 v[214:217], v152 offset:39936
	global_load_lds_dwordx4 v[228:229], off
	v_lshl_add_u64 v[228:229], s[38:39], 0, v[132:133]
	s_mov_b32 m0, s53
	s_nop 0
	global_load_lds_dwordx4 v[228:229], off
	s_waitcnt vmcnt(8)
	s_waitcnt lgkmcnt(0)
	s_barrier
	s_setprio 1
	s_waitcnt lgkmcnt(0)
	v_mfma_f32_16x16x32_bf16 v[126:129], v[154:157], v[186:189], v[126:129]
	v_mfma_f32_16x16x32_bf16 v[126:129], v[158:161], v[190:193], v[126:129]
	v_mfma_f32_16x16x32_bf16 v[122:125], v[162:165], v[186:189], v[122:125]
	v_mfma_f32_16x16x32_bf16 v[122:125], v[166:169], v[190:193], v[122:125]
	v_mfma_f32_16x16x32_bf16 v[118:121], v[170:173], v[186:189], v[118:121]
	v_mfma_f32_16x16x32_bf16 v[118:121], v[174:177], v[190:193], v[118:121]
	v_mfma_f32_16x16x32_bf16 v[114:117], v[178:181], v[186:189], v[114:117]
	v_mfma_f32_16x16x32_bf16 v[114:117], v[182:185], v[190:193], v[114:117]
	v_mfma_f32_16x16x32_bf16 v[110:113], v[154:157], v[194:197], v[110:113]
	v_mfma_f32_16x16x32_bf16 v[110:113], v[158:161], v[198:201], v[110:113]
	v_mfma_f32_16x16x32_bf16 v[106:109], v[162:165], v[194:197], v[106:109]
	v_mfma_f32_16x16x32_bf16 v[106:109], v[166:169], v[198:201], v[106:109]
	v_mfma_f32_16x16x32_bf16 v[102:105], v[170:173], v[194:197], v[102:105]
	v_mfma_f32_16x16x32_bf16 v[102:105], v[174:177], v[198:201], v[102:105]
	v_mfma_f32_16x16x32_bf16 v[98:101], v[178:181], v[194:197], v[98:101]
	v_mfma_f32_16x16x32_bf16 v[98:101], v[182:185], v[198:201], v[98:101]
	s_setprio 0
	s_setprio 1
	v_mfma_f32_16x16x32_bf16 v[94:97], v[154:157], v[202:205], v[94:97]
	v_mfma_f32_16x16x32_bf16 v[94:97], v[158:161], v[206:209], v[94:97]
	v_mfma_f32_16x16x32_bf16 v[90:93], v[162:165], v[202:205], v[90:93]
	v_mfma_f32_16x16x32_bf16 v[90:93], v[166:169], v[206:209], v[90:93]
	v_mfma_f32_16x16x32_bf16 v[86:89], v[170:173], v[202:205], v[86:89]
	v_mfma_f32_16x16x32_bf16 v[86:89], v[174:177], v[206:209], v[86:89]
	v_mfma_f32_16x16x32_bf16 v[82:85], v[178:181], v[202:205], v[82:85]
	v_mfma_f32_16x16x32_bf16 v[82:85], v[182:185], v[206:209], v[82:85]
	v_mfma_f32_16x16x32_bf16 v[78:81], v[154:157], v[210:213], v[78:81]
	v_mfma_f32_16x16x32_bf16 v[78:81], v[158:161], v[214:217], v[78:81]
	v_mfma_f32_16x16x32_bf16 v[74:77], v[162:165], v[210:213], v[74:77]
	v_mfma_f32_16x16x32_bf16 v[74:77], v[166:169], v[214:217], v[74:77]
	v_mfma_f32_16x16x32_bf16 v[70:73], v[170:173], v[210:213], v[70:73]
	v_mfma_f32_16x16x32_bf16 v[70:73], v[174:177], v[214:217], v[70:73]
	v_mfma_f32_16x16x32_bf16 v[66:69], v[178:181], v[210:213], v[66:69]
	v_mfma_f32_16x16x32_bf16 v[66:69], v[182:185], v[214:217], v[66:69]
	s_setprio 0
	s_barrier
	s_add_i32 s38, s67, s48
	v_lshl_add_u64 v[220:221], v[220:221], 0, s[16:17]
	s_mov_b32 m0, s38
	ds_read_b128 v[186:189], v152 offset:49152
	ds_read_b128 v[190:193], v152 offset:50176
	ds_read_b128 v[194:197], v152 offset:51200
	ds_read_b128 v[198:201], v152 offset:52224
	ds_read_b128 v[202:205], v152 offset:53248
	ds_read_b128 v[206:209], v152 offset:54272
	ds_read_b128 v[210:213], v152 offset:55296
	ds_read_b128 v[214:217], v152 offset:56320
	global_load_lds_dwordx4 v[220:221], off
	s_add_i32 m0, s38, 0x2000
	s_add_u32 s36, s36, 0x80080
	v_lshl_add_u64 v[220:221], v[222:223], 0, s[16:17]
	s_addc_u32 s37, s37, 0
	s_add_i32 s38, s68, s48
	global_load_lds_dwordx4 v[220:221], off
	v_lshl_add_u64 v[220:221], s[36:37], 0, v[134:135]
	s_mov_b32 m0, s38
	s_nop 0
	global_load_lds_dwordx4 v[220:221], off
	v_lshl_add_u64 v[220:221], s[36:37], 0, v[130:131]
	s_add_i32 m0, s38, 0x2000
	s_nop 0
	global_load_lds_dwordx4 v[220:221], off
	v_lshl_add_u64 v[220:221], v[224:225], 0, s[16:17]
	s_mov_b32 m0, s57
	s_nop 0
	global_load_lds_dwordx4 v[220:221], off
	v_lshl_add_u64 v[220:221], v[226:227], 0, s[16:17]
	s_mov_b32 m0, s58
	s_nop 0
	global_load_lds_dwordx4 v[220:221], off
	s_waitcnt vmcnt(8)
	s_waitcnt lgkmcnt(0)
	s_barrier
	s_setprio 1
	s_waitcnt lgkmcnt(0)
	v_mfma_f32_16x16x32_bf16 v[62:65], v[154:157], v[186:189], v[62:65]
	v_mfma_f32_16x16x32_bf16 v[62:65], v[158:161], v[190:193], v[62:65]
	v_mfma_f32_16x16x32_bf16 v[58:61], v[162:165], v[186:189], v[58:61]
	v_mfma_f32_16x16x32_bf16 v[58:61], v[166:169], v[190:193], v[58:61]
	v_mfma_f32_16x16x32_bf16 v[54:57], v[170:173], v[186:189], v[54:57]
	v_mfma_f32_16x16x32_bf16 v[54:57], v[174:177], v[190:193], v[54:57]
	v_mfma_f32_16x16x32_bf16 v[50:53], v[178:181], v[186:189], v[50:53]
	v_mfma_f32_16x16x32_bf16 v[50:53], v[182:185], v[190:193], v[50:53]
	v_mfma_f32_16x16x32_bf16 v[46:49], v[154:157], v[194:197], v[46:49]
	v_mfma_f32_16x16x32_bf16 v[46:49], v[158:161], v[198:201], v[46:49]
	v_mfma_f32_16x16x32_bf16 v[42:45], v[162:165], v[194:197], v[42:45]
	v_mfma_f32_16x16x32_bf16 v[42:45], v[166:169], v[198:201], v[42:45]
	v_mfma_f32_16x16x32_bf16 v[38:41], v[170:173], v[194:197], v[38:41]
	v_mfma_f32_16x16x32_bf16 v[38:41], v[174:177], v[198:201], v[38:41]
	v_mfma_f32_16x16x32_bf16 v[34:37], v[178:181], v[194:197], v[34:37]
	v_mfma_f32_16x16x32_bf16 v[34:37], v[182:185], v[198:201], v[34:37]
	s_setprio 0
	s_setprio 1
	v_mfma_f32_16x16x32_bf16 v[30:33], v[154:157], v[202:205], v[30:33]
	v_mfma_f32_16x16x32_bf16 v[30:33], v[158:161], v[206:209], v[30:33]
	v_mfma_f32_16x16x32_bf16 v[26:29], v[162:165], v[202:205], v[26:29]
	v_mfma_f32_16x16x32_bf16 v[26:29], v[166:169], v[206:209], v[26:29]
	v_mfma_f32_16x16x32_bf16 v[22:25], v[170:173], v[202:205], v[22:25]
	v_mfma_f32_16x16x32_bf16 v[22:25], v[174:177], v[206:209], v[22:25]
	v_mfma_f32_16x16x32_bf16 v[18:21], v[178:181], v[202:205], v[18:21]
	v_mfma_f32_16x16x32_bf16 v[18:21], v[182:185], v[206:209], v[18:21]
	v_mfma_f32_16x16x32_bf16 v[14:17], v[154:157], v[210:213], v[14:17]
	v_mfma_f32_16x16x32_bf16 v[14:17], v[158:161], v[214:217], v[14:17]
	v_mfma_f32_16x16x32_bf16 v[10:13], v[162:165], v[210:213], v[10:13]
	v_mfma_f32_16x16x32_bf16 v[10:13], v[166:169], v[214:217], v[10:13]
	v_mfma_f32_16x16x32_bf16 v[6:9], v[170:173], v[210:213], v[6:9]
	v_mfma_f32_16x16x32_bf16 v[6:9], v[174:177], v[214:217], v[6:9]
	v_mfma_f32_16x16x32_bf16 v[2:5], v[178:181], v[210:213], v[2:5]
	v_mfma_f32_16x16x32_bf16 v[2:5], v[182:185], v[214:217], v[2:5]
	s_setprio 0
	s_barrier
	s_add_i32 s66, s66, 2
	s_add_u32 s64, s64, 0x100
	s_addc_u32 s65, s65, 0
	s_add_u32 s30, s30, 0x100
	s_addc_u32 s31, s31, 0
	s_cmp_gt_u32 s66, 29
	s_cbranch_scc0 .LBB0_1297
	s_and_b64 vcc, exec, s[18:19]
	s_cbranch_vccz .LBB0_1300
	s_barrier

.LBB0_1379:
	ds_read_b128 v[150:153], v216
	ds_read_b128 v[154:157], v216 offset:1024
	ds_read_b128 v[158:161], v216 offset:2048
	ds_read_b128 v[162:165], v216 offset:3072
	ds_read_b128 v[134:137], v217
	ds_read_b128 v[138:141], v217 offset:1024
	ds_read_b128 v[142:145], v217 offset:2048
	ds_read_b128 v[146:149], v217 offset:3072
	s_mov_b64 s[6:7], s[26:27]
	s_add_u32 s26, s6, 0x100
	s_addc_u32 s27, s7, 0
	s_cmpk_eq_i32 s69, 0x52
	s_cselect_b32 s37, s23, s27
	s_cselect_b32 s36, s22, s26
	s_cselect_b32 s31, s25, s35
	s_cselect_b32 s30, s24, s34
	v_lshl_add_u64 v[4:5], s[6:7], 0, v[204:205]
	s_add_i32 m0, s48, 0xc000
	s_waitcnt lgkmcnt(0)
	ds_read_b128 v[166:169], v219
	ds_read_b128 v[170:173], v219 offset:1024
	ds_read_b128 v[174:177], v219 offset:2048
	ds_read_b128 v[178:181], v219 offset:3072
	ds_read_b128 v[182:185], v219 offset:4096
	ds_read_b128 v[186:189], v219 offset:5120
	ds_read_b128 v[190:193], v219 offset:6144
	ds_read_b128 v[194:197], v219 offset:7168
	global_load_lds_dwordx4 v[4:5], off
	v_lshl_add_u64 v[4:5], s[6:7], 0, v[202:203]
	s_add_i32 m0, s48, 0xe000
	s_nop 0
	global_load_lds_dwordx4 v[4:5], off
	s_waitcnt vmcnt(8)
	s_waitcnt lgkmcnt(0)
	s_barrier
	s_setprio 1
	s_waitcnt lgkmcnt(0)
	v_mfma_f32_16x16x32_bf16 v[130:133], v[150:153], v[166:169], v[130:133]
	v_mfma_f32_16x16x32_bf16 v[130:133], v[154:157], v[170:173], v[130:133]
	v_mfma_f32_16x16x32_bf16 v[126:129], v[158:161], v[166:169], v[126:129]
	v_mfma_f32_16x16x32_bf16 v[126:129], v[162:165], v[170:173], v[126:129]
	v_mfma_f32_16x16x32_bf16 v[110:113], v[134:137], v[166:169], v[110:113]
	v_mfma_f32_16x16x32_bf16 v[110:113], v[138:141], v[170:173], v[110:113]
	v_mfma_f32_16x16x32_bf16 v[102:105], v[142:145], v[166:169], v[102:105]
	v_mfma_f32_16x16x32_bf16 v[102:105], v[146:149], v[170:173], v[102:105]
	v_mfma_f32_16x16x32_bf16 v[122:125], v[150:153], v[174:177], v[122:125]
	v_mfma_f32_16x16x32_bf16 v[122:125], v[154:157], v[178:181], v[122:125]
	v_mfma_f32_16x16x32_bf16 v[118:121], v[158:161], v[174:177], v[118:121]
	v_mfma_f32_16x16x32_bf16 v[118:121], v[162:165], v[178:181], v[118:121]
	v_mfma_f32_16x16x32_bf16 v[94:97], v[134:137], v[174:177], v[94:97]
	v_mfma_f32_16x16x32_bf16 v[94:97], v[138:141], v[178:181], v[94:97]
	v_mfma_f32_16x16x32_bf16 v[90:93], v[142:145], v[174:177], v[90:93]
	v_mfma_f32_16x16x32_bf16 v[90:93], v[146:149], v[178:181], v[90:93]
	s_setprio 0
	s_setprio 1
	v_mfma_f32_16x16x32_bf16 v[114:117], v[150:153], v[182:185], v[114:117]
	v_mfma_f32_16x16x32_bf16 v[114:117], v[154:157], v[186:189], v[114:117]
	v_mfma_f32_16x16x32_bf16 v[106:109], v[158:161], v[182:185], v[106:109]
	v_mfma_f32_16x16x32_bf16 v[106:109], v[162:165], v[186:189], v[106:109]
	v_mfma_f32_16x16x32_bf16 v[82:85], v[134:137], v[182:185], v[82:85]
	v_mfma_f32_16x16x32_bf16 v[82:85], v[138:141], v[186:189], v[82:85]
	v_mfma_f32_16x16x32_bf16 v[78:81], v[142:145], v[182:185], v[78:81]
	v_mfma_f32_16x16x32_bf16 v[78:81], v[146:149], v[186:189], v[78:81]
	v_mfma_f32_16x16x32_bf16 v[98:101], v[150:153], v[190:193], v[98:101]
	v_mfma_f32_16x16x32_bf16 v[98:101], v[154:157], v[194:197], v[98:101]
	v_mfma_f32_16x16x32_bf16 v[86:89], v[158:161], v[190:193], v[86:89]
	v_mfma_f32_16x16x32_bf16 v[86:89], v[162:165], v[194:197], v[86:89]
	v_mfma_f32_16x16x32_bf16 v[74:77], v[134:137], v[190:193], v[74:77]
	v_mfma_f32_16x16x32_bf16 v[74:77], v[138:141], v[194:197], v[74:77]
	v_mfma_f32_16x16x32_bf16 v[70:73], v[142:145], v[190:193], v[70:73]
	v_mfma_f32_16x16x32_bf16 v[70:73], v[146:149], v[194:197], v[70:73]
	s_setprio 0
	s_barrier
	s_add_i32 s6, s13, s47
	v_lshl_add_u64 v[4:5], s[30:31], 0, v[198:199]
	s_mov_b32 m0, s6
	ds_read_b128 v[190:193], v219 offset:16384
	ds_read_b128 v[194:197], v219 offset:17408
	ds_read_b128 v[182:185], v219 offset:18432
	ds_read_b128 v[186:189], v219 offset:19456
	ds_read_b128 v[174:177], v219 offset:20480
	ds_read_b128 v[178:181], v219 offset:21504
	ds_read_b128 v[166:169], v219 offset:22528
	ds_read_b128 v[170:173], v219 offset:23552
	global_load_lds_dwordx4 v[4:5], off
	s_add_i32 m0, s6, 0x2000
	s_add_u32 s6, s30, 0x158000
	v_lshl_add_u64 v[208:209], s[30:31], 0, v[200:201]
	s_addc_u32 s7, s31, 0
	s_add_i32 s70, s62, s47
	global_load_lds_dwordx4 v[208:209], off
	v_lshl_add_u64 v[210:211], s[6:7], 0, v[198:199]
	s_mov_b32 m0, s70
	v_lshl_add_u64 v[212:213], s[36:37], 0, v[200:201]
	global_load_lds_dwordx4 v[210:211], off
	v_lshl_add_u64 v[210:211], s[6:7], 0, v[200:201]
	s_add_i32 m0, s70, 0x2000
	v_cmp_ne_u32_e64 s[6:7], 1, v220
	global_load_lds_dwordx4 v[210:211], off
	v_lshl_add_u64 v[210:211], s[36:37], 0, v[198:199]
	s_mov_b32 m0, s48
	s_andn2_b64 vcc, exec, s[28:29]
	global_load_lds_dwordx4 v[210:211], off
	s_mov_b32 m0, s49
	s_nop 0
	global_load_lds_dwordx4 v[212:213], off
	s_waitcnt vmcnt(8)
	s_waitcnt lgkmcnt(0)
	s_barrier
	s_cbranch_vccnz .LBB0_1381
	s_setprio 1
	s_waitcnt lgkmcnt(0)
	v_mfma_f32_16x16x32_bf16 v[66:69], v[150:153], v[190:193], v[66:69]
	v_mfma_f32_16x16x32_bf16 v[66:69], v[154:157], v[194:197], v[66:69]
	v_mfma_f32_16x16x32_bf16 v[62:65], v[158:161], v[190:193], v[62:65]
	v_mfma_f32_16x16x32_bf16 v[62:65], v[162:165], v[194:197], v[62:65]
	v_mfma_f32_16x16x32_bf16 v[54:57], v[134:137], v[190:193], v[54:57]
	v_mfma_f32_16x16x32_bf16 v[54:57], v[138:141], v[194:197], v[54:57]
	v_mfma_f32_16x16x32_bf16 v[46:49], v[142:145], v[190:193], v[46:49]
	v_mfma_f32_16x16x32_bf16 v[46:49], v[146:149], v[194:197], v[46:49]
	v_mfma_f32_16x16x32_bf16 v[58:61], v[150:153], v[182:185], v[58:61]
	v_mfma_f32_16x16x32_bf16 v[58:61], v[154:157], v[186:189], v[58:61]
	v_mfma_f32_16x16x32_bf16 v[50:53], v[158:161], v[182:185], v[50:53]
	v_mfma_f32_16x16x32_bf16 v[50:53], v[162:165], v[186:189], v[50:53]
	v_mfma_f32_16x16x32_bf16 v[38:41], v[134:137], v[182:185], v[38:41]
	v_mfma_f32_16x16x32_bf16 v[38:41], v[138:141], v[186:189], v[38:41]
	v_mfma_f32_16x16x32_bf16 v[30:33], v[142:145], v[182:185], v[30:33]
	v_mfma_f32_16x16x32_bf16 v[30:33], v[146:149], v[186:189], v[30:33]
	s_setprio 0
	s_setprio 1
	v_mfma_f32_16x16x32_bf16 v[42:45], v[150:153], v[174:177], v[42:45]
	v_mfma_f32_16x16x32_bf16 v[42:45], v[154:157], v[178:181], v[42:45]
	v_mfma_f32_16x16x32_bf16 v[34:37], v[158:161], v[174:177], v[34:37]
	v_mfma_f32_16x16x32_bf16 v[34:37], v[162:165], v[178:181], v[34:37]
	v_mfma_f32_16x16x32_bf16 v[26:29], v[134:137], v[174:177], v[26:29]
	v_mfma_f32_16x16x32_bf16 v[26:29], v[138:141], v[178:181], v[26:29]
	v_mfma_f32_16x16x32_bf16 v[18:21], v[142:145], v[174:177], v[18:21]
	v_mfma_f32_16x16x32_bf16 v[18:21], v[146:149], v[178:181], v[18:21]
	v_mfma_f32_16x16x32_bf16 v[22:25], v[150:153], v[166:169], v[22:25]
	v_mfma_f32_16x16x32_bf16 v[22:25], v[154:157], v[170:173], v[22:25]
	v_mfma_f32_16x16x32_bf16 v[14:17], v[158:161], v[166:169], v[14:17]
	v_mfma_f32_16x16x32_bf16 v[14:17], v[162:165], v[170:173], v[14:17]
	v_mfma_f32_16x16x32_bf16 v[10:13], v[134:137], v[166:169], v[10:13]
	v_mfma_f32_16x16x32_bf16 v[10:13], v[138:141], v[170:173], v[10:13]
	v_mfma_f32_16x16x32_bf16 v[6:9], v[142:145], v[166:169], v[6:9]
	v_mfma_f32_16x16x32_bf16 v[6:9], v[146:149], v[170:173], v[6:9]
	s_setprio 0
.LBB0_1381:
	s_barrier
	s_add_i32 s70, 16, 0x18000
	v_add_u32_e32 v2, s70, v215
	s_add_i32 s71, 16, 0x1c000
	ds_read_b128 v[150:153], v2
	ds_read_b128 v[154:157], v2 offset:1024
	ds_read_b128 v[158:161], v2 offset:2048
	ds_read_b128 v[162:165], v2 offset:3072
	v_add_u32_e32 v2, s71, v215
	ds_read_b128 v[134:137], v2
	ds_read_b128 v[138:141], v2 offset:1024
	ds_read_b128 v[142:145], v2 offset:2048
	ds_read_b128 v[146:149], v2 offset:3072
	s_add_u32 s36, s36, 0x158000
	s_addc_u32 s37, s37, 0
	s_mov_b32 m0, s50
	v_lshl_add_u64 v[222:223], s[36:37], 0, v[198:199]
	s_waitcnt lgkmcnt(0)
	ds_read_b128 v[166:169], v219 offset:32768
	ds_read_b128 v[170:173], v219 offset:33792
	ds_read_b128 v[174:177], v219 offset:34816
	ds_read_b128 v[178:181], v219 offset:35840
	ds_read_b128 v[182:185], v219 offset:36864
	ds_read_b128 v[186:189], v219 offset:37888
	ds_read_b128 v[190:193], v219 offset:38912
	ds_read_b128 v[194:197], v219 offset:39936
	global_load_lds_dwordx4 v[222:223], off
	v_lshl_add_u64 v[222:223], s[36:37], 0, v[200:201]
	s_mov_b32 m0, s51
	s_nop 0
	global_load_lds_dwordx4 v[222:223], off
	s_waitcnt vmcnt(8)
	s_waitcnt lgkmcnt(0)
	s_barrier
	s_setprio 1
	s_waitcnt lgkmcnt(0)
	v_mfma_f32_16x16x32_bf16 v[130:133], v[150:153], v[166:169], v[130:133]
	v_mfma_f32_16x16x32_bf16 v[130:133], v[154:157], v[170:173], v[130:133]
	v_mfma_f32_16x16x32_bf16 v[126:129], v[158:161], v[166:169], v[126:129]
	v_mfma_f32_16x16x32_bf16 v[126:129], v[162:165], v[170:173], v[126:129]
	v_mfma_f32_16x16x32_bf16 v[110:113], v[134:137], v[166:169], v[110:113]
	v_mfma_f32_16x16x32_bf16 v[110:113], v[138:141], v[170:173], v[110:113]
	v_mfma_f32_16x16x32_bf16 v[102:105], v[142:145], v[166:169], v[102:105]
	v_mfma_f32_16x16x32_bf16 v[102:105], v[146:149], v[170:173], v[102:105]
	v_mfma_f32_16x16x32_bf16 v[122:125], v[150:153], v[174:177], v[122:125]
	v_mfma_f32_16x16x32_bf16 v[122:125], v[154:157], v[178:181], v[122:125]
	v_mfma_f32_16x16x32_bf16 v[118:121], v[158:161], v[174:177], v[118:121]
	v_mfma_f32_16x16x32_bf16 v[118:121], v[162:165], v[178:181], v[118:121]
	v_mfma_f32_16x16x32_bf16 v[94:97], v[134:137], v[174:177], v[94:97]
	v_mfma_f32_16x16x32_bf16 v[94:97], v[138:141], v[178:181], v[94:97]
	v_mfma_f32_16x16x32_bf16 v[90:93], v[142:145], v[174:177], v[90:93]
	v_mfma_f32_16x16x32_bf16 v[90:93], v[146:149], v[178:181], v[90:93]
	s_setprio 0
	s_setprio 1
	v_mfma_f32_16x16x32_bf16 v[114:117], v[150:153], v[182:185], v[114:117]
	v_mfma_f32_16x16x32_bf16 v[114:117], v[154:157], v[186:189], v[114:117]
	v_mfma_f32_16x16x32_bf16 v[106:109], v[158:161], v[182:185], v[106:109]
	v_mfma_f32_16x16x32_bf16 v[106:109], v[162:165], v[186:189], v[106:109]
	v_mfma_f32_16x16x32_bf16 v[82:85], v[134:137], v[182:185], v[82:85]
	v_mfma_f32_16x16x32_bf16 v[82:85], v[138:141], v[186:189], v[82:85]
	v_mfma_f32_16x16x32_bf16 v[78:81], v[142:145], v[182:185], v[78:81]
	v_mfma_f32_16x16x32_bf16 v[78:81], v[146:149], v[186:189], v[78:81]
	v_mfma_f32_16x16x32_bf16 v[98:101], v[150:153], v[190:193], v[98:101]
	v_mfma_f32_16x16x32_bf16 v[98:101], v[154:157], v[194:197], v[98:101]
	v_mfma_f32_16x16x32_bf16 v[86:89], v[158:161], v[190:193], v[86:89]
	v_mfma_f32_16x16x32_bf16 v[86:89], v[162:165], v[194:197], v[86:89]
	v_mfma_f32_16x16x32_bf16 v[74:77], v[134:137], v[190:193], v[74:77]
	v_mfma_f32_16x16x32_bf16 v[74:77], v[138:141], v[194:197], v[74:77]
	v_mfma_f32_16x16x32_bf16 v[70:73], v[142:145], v[190:193], v[70:73]
	v_mfma_f32_16x16x32_bf16 v[70:73], v[146:149], v[194:197], v[70:73]
	s_setprio 0
	s_barrier
	s_add_i32 s36, s70, s47
	v_lshl_add_u64 v[4:5], v[4:5], 0, s[10:11]
	s_mov_b32 m0, s36
	ds_read_b128 v[190:193], v219 offset:49152
	ds_read_b128 v[194:197], v219 offset:50176
	ds_read_b128 v[182:185], v219 offset:51200
	ds_read_b128 v[186:189], v219 offset:52224
	ds_read_b128 v[174:177], v219 offset:53248
	ds_read_b128 v[178:181], v219 offset:54272
	ds_read_b128 v[166:169], v219 offset:55296
	ds_read_b128 v[170:173], v219 offset:56320
	global_load_lds_dwordx4 v[4:5], off
	s_add_i32 m0, s36, 0x2000
	s_add_u32 s30, s30, 0x158080
	v_lshl_add_u64 v[4:5], v[208:209], 0, s[10:11]
	s_addc_u32 s31, s31, 0
	s_add_i32 s36, s71, s47
	global_load_lds_dwordx4 v[4:5], off
	v_lshl_add_u64 v[4:5], s[30:31], 0, v[198:199]
	s_mov_b32 m0, s36
	s_and_b64 vcc, exec, s[6:7]
	global_load_lds_dwordx4 v[4:5], off
	v_lshl_add_u64 v[4:5], s[30:31], 0, v[200:201]
	s_add_i32 m0, s36, 0x2000
	s_nop 0
	global_load_lds_dwordx4 v[4:5], off
	v_lshl_add_u64 v[4:5], v[210:211], 0, s[10:11]
	s_mov_b32 m0, s57
	s_nop 0
	global_load_lds_dwordx4 v[4:5], off
	v_lshl_add_u64 v[4:5], v[212:213], 0, s[10:11]
	s_mov_b32 m0, s58
	s_nop 0
	global_load_lds_dwordx4 v[4:5], off
	s_waitcnt vmcnt(8)
	s_waitcnt lgkmcnt(0)
	s_barrier
	s_cbranch_vccnz .LBB0_1378
	s_setprio 1
	s_waitcnt lgkmcnt(0)
	v_mfma_f32_16x16x32_bf16 v[66:69], v[150:153], v[190:193], v[66:69]
	v_mfma_f32_16x16x32_bf16 v[66:69], v[154:157], v[194:197], v[66:69]
	v_mfma_f32_16x16x32_bf16 v[62:65], v[158:161], v[190:193], v[62:65]
	v_mfma_f32_16x16x32_bf16 v[62:65], v[162:165], v[194:197], v[62:65]
	v_mfma_f32_16x16x32_bf16 v[54:57], v[134:137], v[190:193], v[54:57]
	v_mfma_f32_16x16x32_bf16 v[54:57], v[138:141], v[194:197], v[54:57]
	v_mfma_f32_16x16x32_bf16 v[46:49], v[142:145], v[190:193], v[46:49]
	v_mfma_f32_16x16x32_bf16 v[46:49], v[146:149], v[194:197], v[46:49]
	v_mfma_f32_16x16x32_bf16 v[58:61], v[150:153], v[182:185], v[58:61]
	v_mfma_f32_16x16x32_bf16 v[58:61], v[154:157], v[186:189], v[58:61]
	v_mfma_f32_16x16x32_bf16 v[50:53], v[158:161], v[182:185], v[50:53]
	v_mfma_f32_16x16x32_bf16 v[50:53], v[162:165], v[186:189], v[50:53]
	v_mfma_f32_16x16x32_bf16 v[38:41], v[134:137], v[182:185], v[38:41]
	v_mfma_f32_16x16x32_bf16 v[38:41], v[138:141], v[186:189], v[38:41]
	v_mfma_f32_16x16x32_bf16 v[30:33], v[142:145], v[182:185], v[30:33]
	v_mfma_f32_16x16x32_bf16 v[30:33], v[146:149], v[186:189], v[30:33]
	s_setprio 0
	s_setprio 1
	v_mfma_f32_16x16x32_bf16 v[42:45], v[150:153], v[174:177], v[42:45]
	v_mfma_f32_16x16x32_bf16 v[42:45], v[154:157], v[178:181], v[42:45]
	v_mfma_f32_16x16x32_bf16 v[34:37], v[158:161], v[174:177], v[34:37]
	v_mfma_f32_16x16x32_bf16 v[34:37], v[162:165], v[178:181], v[34:37]
	v_mfma_f32_16x16x32_bf16 v[26:29], v[134:137], v[174:177], v[26:29]
	v_mfma_f32_16x16x32_bf16 v[26:29], v[138:141], v[178:181], v[26:29]
	v_mfma_f32_16x16x32_bf16 v[18:21], v[142:145], v[174:177], v[18:21]
	v_mfma_f32_16x16x32_bf16 v[18:21], v[146:149], v[178:181], v[18:21]
	v_mfma_f32_16x16x32_bf16 v[22:25], v[150:153], v[166:169], v[22:25]
	v_mfma_f32_16x16x32_bf16 v[22:25], v[154:157], v[170:173], v[22:25]
	v_mfma_f32_16x16x32_bf16 v[14:17], v[158:161], v[166:169], v[14:17]
	v_mfma_f32_16x16x32_bf16 v[14:17], v[162:165], v[170:173], v[14:17]
	v_mfma_f32_16x16x32_bf16 v[10:13], v[134:137], v[166:169], v[10:13]
	v_mfma_f32_16x16x32_bf16 v[10:13], v[138:141], v[170:173], v[10:13]
	v_mfma_f32_16x16x32_bf16 v[4:7], v[142:145], v[166:169], v[6:9]
	v_mfma_f32_16x16x32_bf16 v[6:9], v[146:149], v[170:173], v[4:7]
	s_setprio 0
	s_branch .LBB0_1378
